# dynamic row tickets in ROW1..ROW3 now use 16 counters per phase (wave index x workgroup parity) instead of 8, halving same-address atomic traffic
# speedup vs baseline: 1.0099x; 1.0099x over previous
.LBB0_735:
	v_lshrrev_b32_e32 v0, 6, v128
	s_waitcnt vmcnt(0)
	v_lshl_add_u32 v130, s34, 3, v0
	v_lshlrev_b32_e32 v236, 8, v0
	v_add_u32_e32 v236, 0x480, v236
	s_and_b32 s86, s34, 1
	s_lshl_b32 s83, s86, 11
	v_add_u32_e32 v236, s83, v236
	s_lshl_b32 s82, s34, 3
	s_movk_i32 s0, 0x2400
	v_cmp_gt_i32_e32 vcc, s0, v130
	s_and_saveexec_b64 s[0:1], vcc
	s_cbranch_execz .LBB0_742
	v_lshlrev_b32_e32 v0, 2, v128
	v_and_b32_e32 v132, 0xfc, v0
	v_mbcnt_lo_u32_b32 v0, -1, 0
	v_mbcnt_hi_u32_b32 v0, -1, v0
	v_and_b32_e32 v1, 64, v0
	v_add_u32_e32 v1, 64, v1
	v_xor_b32_e32 v2, 1, v0
	v_cmp_lt_i32_e32 vcc, v2, v1
	s_lshl_b32 s6, s94, 3
	s_add_u32 s8, s50, 0xc604000
	v_cndmask_b32_e32 v2, v0, v2, vcc
	v_lshlrev_b32_e32 v129, 2, v2
	v_xor_b32_e32 v2, 2, v0
	v_cmp_lt_i32_e32 vcc, v2, v1
	s_addc_u32 s9, s51, 0
	s_add_u32 s10, s50, 0xff05000
	v_cndmask_b32_e32 v2, v0, v2, vcc
	v_lshlrev_b32_e32 v133, 2, v2
	v_xor_b32_e32 v2, 4, v0
	v_cmp_lt_i32_e32 vcc, v2, v1
	s_addc_u32 s11, s51, 0
	s_add_u32 s12, s50, 0x1aa05000
	v_cndmask_b32_e32 v2, v0, v2, vcc
	v_lshlrev_b32_e32 v137, 2, v2
	v_xor_b32_e32 v2, 8, v0
	v_cmp_lt_i32_e32 vcc, v2, v1
	s_addc_u32 s13, s51, 0
	s_add_u32 s14, s50, 0x12305000
	v_cndmask_b32_e32 v2, v0, v2, vcc
	v_lshlrev_b32_e32 v139, 2, v2
	v_xor_b32_e32 v2, 16, v0
	v_cmp_lt_i32_e32 vcc, v2, v1
	s_addc_u32 s15, s51, 0
	s_add_u32 s26, s50, 0x1ce05000
	v_cndmask_b32_e32 v2, v0, v2, vcc
	v_lshlrev_b32_e32 v141, 2, v2
	v_xor_b32_e32 v2, 32, v0
	v_cmp_lt_i32_e32 vcc, v2, v1
	v_mov_b32_e32 v135, 0
	v_lshlrev_b32_e32 v134, 1, v132
	v_cndmask_b32_e32 v0, v0, v2, vcc
	s_addc_u32 s27, s51, 0
	v_lshlrev_b32_e32 v143, 2, v0
	v_lshl_add_u64 v[0:1], s[50:51], 0, v[134:135]
	s_mov_b64 s[4:5], 0xdb05000
	v_ashrrev_i32_e32 v131, 31, v130
	s_ashr_i32 s7, s6, 31
	v_or_b32_e32 v136, 0x100, v132
	v_or_b32_e32 v138, 0x200, v132
	v_or_b32_e32 v140, 0x300, v132
	v_or_b32_e32 v142, 0x400, v132
	v_or_b32_e32 v144, 0x500, v132
	v_or_b32_e32 v146, 0x600, v132
	v_or_b32_e32 v148, 0x700, v132
	v_lshl_add_u64 v[150:151], v[0:1], 0, s[4:5]
	v_lshlrev_b64 v[152:153], 13, v[130:131]
	s_lshl_b64 s[28:29], s[6:7], 13
	s_mov_b64 s[30:31], 0
	s_movk_i32 s33, 0x2000
	s_movk_i32 s35, 0x1fff
	s_mov_b32 s58, 0x12000
	s_mov_b64 s[52:53], 0x4000
	s_mov_b64 s[54:55], 0x8000
	s_mov_b64 s[56:57], 0x6000
	v_mov_b32_e32 v145, 0x358637bd
	s_mov_b32 s59, 0x800000
	s_movk_i32 s60, 0x23ff
	s_branch .LBB0_738
.LBB0_737:
	s_or_b64 exec, exec, s[4:5]
	v_lshrrev_b32_e32 v32, 3, v134
	v_lshlrev_b32_e32 v134, 2, v132
	v_lshl_add_u64 v[2:3], v[0:1], 0, v[134:135]
	v_lshlrev_b32_e32 v162, 2, v142
	v_mov_b32_e32 v163, v135
	global_load_dwordx4 v[24:27], v[2:3], off
	global_load_dwordx4 v[20:23], v[2:3], off offset:1024
	global_load_dwordx4 v[16:19], v[2:3], off offset:2048
	global_load_dwordx4 v[12:15], v[2:3], off offset:3072
	v_lshl_add_u64 v[2:3], v[0:1], 0, v[162:163]
	v_lshlrev_b32_e32 v160, 2, v144
	v_mov_b32_e32 v161, v135
	v_lshlrev_b32_e32 v158, 2, v146
	v_mov_b32_e32 v159, v135
	v_lshlrev_b32_e32 v156, 2, v148
	v_mov_b32_e32 v157, v135
	v_lshl_add_u64 v[4:5], v[0:1], 0, v[160:161]
	global_load_dwordx4 v[28:31], v[2:3], off
	global_load_dwordx4 v[8:11], v[4:5], off
	v_lshl_add_u64 v[2:3], v[0:1], 0, v[158:159]
	v_lshl_add_u64 v[0:1], v[0:1], 0, v[156:157]
	global_load_dwordx4 v[4:7], v[2:3], off
	s_nop 0
	global_load_dwordx4 v[0:3], v[0:1], off
	v_ashrrev_i32_e32 v33, 12, v130
	v_add_u32_e32 v32, 2, v32
	v_cndmask_b32_e32 v34, v32, v33, vcc
	v_mov_b64_e32 v[32:33], s[8:9]
	v_mad_i64_i32 v[64:65], s[4:5], v34, s58, v[32:33]
	v_lshlrev_b64 v[56:57], 11, v[154:155]
	v_or_b32_e32 v32, v56, v132
	v_mov_b32_e32 v33, v57
	v_lshlrev_b64 v[32:33], 1, v[32:33]
	v_lshl_add_u64 v[34:35], s[10:11], 0, v[32:33]
	v_lshl_add_u64 v[36:37], s[14:15], 0, v[32:33]
	v_lshl_add_u64 v[38:39], s[12:13], 0, v[32:33]
	v_lshl_add_u64 v[32:33], s[26:27], 0, v[32:33]
	global_load_dwordx2 v[100:101], v[34:35], off
	global_load_dwordx2 v[102:103], v[36:37], off
	global_load_dwordx2 v[104:105], v[38:39], off
	global_load_dwordx2 v[106:107], v[32:33], off
	v_or_b32_e32 v34, v56, v136
	v_mov_b32_e32 v35, v57
	v_lshl_add_u64 v[58:59], v[64:65], 0, s[52:53]
	v_lshlrev_b64 v[36:37], 1, v[34:35]
	v_lshl_add_u64 v[32:33], v[58:59], 0, v[134:135]
	v_lshl_add_u64 v[38:39], s[10:11], 0, v[36:37]
	global_load_dwordx4 v[32:35], v[32:33], off
	s_nop 0
	global_load_dwordx2 v[108:109], v[38:39], off
	v_lshl_add_u64 v[38:39], s[14:15], 0, v[36:37]
	v_lshl_add_u64 v[40:41], s[12:13], 0, v[36:37]
	v_lshl_add_u64 v[36:37], s[26:27], 0, v[36:37]
	global_load_dwordx2 v[110:111], v[38:39], off
	global_load_dwordx2 v[112:113], v[40:41], off
	global_load_dwordx2 v[114:115], v[36:37], off
	v_or_b32_e32 v38, v56, v138
	v_mov_b32_e32 v39, v57
	v_lshlrev_b32_e32 v66, 2, v136
	v_mov_b32_e32 v67, v135
	v_lshlrev_b64 v[40:41], 1, v[38:39]
	v_lshl_add_u64 v[36:37], v[58:59], 0, v[66:67]
	v_lshl_add_u64 v[42:43], s[10:11], 0, v[40:41]
	global_load_dwordx4 v[36:39], v[36:37], off
	s_nop 0
	global_load_dwordx2 v[116:117], v[42:43], off
	v_lshl_add_u64 v[42:43], s[14:15], 0, v[40:41]
	v_lshl_add_u64 v[44:45], s[12:13], 0, v[40:41]
	v_lshl_add_u64 v[40:41], s[26:27], 0, v[40:41]
	global_load_dwordx2 v[118:119], v[42:43], off
	global_load_dwordx2 v[120:121], v[44:45], off
	global_load_dwordx2 v[122:123], v[40:41], off
	v_or_b32_e32 v42, v56, v140
	v_mov_b32_e32 v43, v57
	v_lshlrev_b32_e32 v68, 2, v138
	v_mov_b32_e32 v69, v135
	v_lshlrev_b64 v[44:45], 1, v[42:43]
	v_lshl_add_u64 v[40:41], v[58:59], 0, v[68:69]
	v_lshl_add_u64 v[46:47], s[10:11], 0, v[44:45]
	global_load_dwordx4 v[40:43], v[40:41], off
	s_nop 0
	global_load_dwordx2 v[124:125], v[46:47], off
	v_lshl_add_u64 v[46:47], s[14:15], 0, v[44:45]
	v_lshl_add_u64 v[48:49], s[12:13], 0, v[44:45]
	v_lshl_add_u64 v[44:45], s[26:27], 0, v[44:45]
	global_load_dwordx2 v[126:127], v[46:47], off
	global_load_dwordx2 v[180:181], v[48:49], off
	global_load_dwordx2 v[182:183], v[44:45], off
	v_or_b32_e32 v46, v56, v142
	v_mov_b32_e32 v47, v57
	v_lshlrev_b32_e32 v70, 2, v140
	v_mov_b32_e32 v71, v135
	v_lshlrev_b64 v[48:49], 1, v[46:47]
	v_lshl_add_u64 v[44:45], v[58:59], 0, v[70:71]
	v_lshl_add_u64 v[50:51], s[10:11], 0, v[48:49]
	global_load_dwordx4 v[44:47], v[44:45], off
	s_nop 0
	global_load_dwordx2 v[184:185], v[50:51], off
	v_lshl_add_u64 v[50:51], s[14:15], 0, v[48:49]
	v_lshl_add_u64 v[52:53], s[12:13], 0, v[48:49]
	v_lshl_add_u64 v[48:49], s[26:27], 0, v[48:49]
	global_load_dwordx2 v[186:187], v[50:51], off
	global_load_dwordx2 v[98:99], v[52:53], off
	global_load_dwordx2 v[96:97], v[48:49], off
	v_or_b32_e32 v50, v56, v144
	v_mov_b32_e32 v51, v57
	v_lshlrev_b64 v[52:53], 1, v[50:51]
	v_lshl_add_u64 v[48:49], v[58:59], 0, v[162:163]
	v_lshl_add_u64 v[54:55], s[10:11], 0, v[52:53]
	global_load_dwordx4 v[48:51], v[48:49], off
	s_nop 0
	global_load_dwordx2 v[92:93], v[54:55], off
	v_lshl_add_u64 v[54:55], s[14:15], 0, v[52:53]
	v_lshl_add_u64 v[60:61], s[12:13], 0, v[52:53]
	v_lshl_add_u64 v[52:53], s[26:27], 0, v[52:53]
	global_load_dwordx2 v[94:95], v[54:55], off
	global_load_dwordx2 v[90:91], v[60:61], off
	global_load_dwordx2 v[88:89], v[52:53], off
	v_or_b32_e32 v54, v56, v146
	v_mov_b32_e32 v55, v57
	v_lshlrev_b64 v[60:61], 1, v[54:55]
	v_lshl_add_u64 v[52:53], v[58:59], 0, v[160:161]
	v_lshl_add_u64 v[62:63], s[10:11], 0, v[60:61]
	v_or_b32_e32 v56, v56, v148
	global_load_dwordx4 v[52:55], v[52:53], off
	s_nop 0
	global_load_dwordx2 v[84:85], v[62:63], off
	v_lshl_add_u64 v[62:63], s[14:15], 0, v[60:61]
	v_lshl_add_u64 v[72:73], s[12:13], 0, v[60:61]
	v_lshl_add_u64 v[60:61], s[26:27], 0, v[60:61]
	v_lshlrev_b64 v[56:57], 1, v[56:57]
	global_load_dwordx2 v[86:87], v[62:63], off
	global_load_dwordx2 v[82:83], v[72:73], off
	global_load_dwordx2 v[80:81], v[60:61], off
	v_lshl_add_u64 v[60:61], v[58:59], 0, v[158:159]
	v_lshl_add_u64 v[72:73], s[10:11], 0, v[56:57]
	global_load_dwordx4 v[60:63], v[60:61], off
	s_nop 0
	global_load_dwordx2 v[76:77], v[72:73], off
	v_lshl_add_u64 v[72:73], s[14:15], 0, v[56:57]
	v_lshl_add_u64 v[74:75], s[12:13], 0, v[56:57]
	v_lshl_add_u64 v[56:57], s[26:27], 0, v[56:57]
	global_load_dwordx2 v[78:79], v[72:73], off
	s_nop 0
	global_load_dwordx2 v[74:75], v[74:75], off
	s_nop 0
	global_load_dwordx2 v[72:73], v[56:57], off
	v_lshl_add_u64 v[56:57], v[58:59], 0, v[156:157]
	global_load_dwordx4 v[56:59], v[56:57], off
	s_waitcnt vmcnt(39)
	v_lshlrev_b32_e32 v166, 16, v100
	v_and_b32_e32 v167, 0xffff0000, v100
	s_waitcnt vmcnt(38)
	v_lshlrev_b32_e32 v168, 16, v102
	v_and_b32_e32 v169, 0xffff0000, v102
	v_lshlrev_b32_e32 v100, 16, v101
	v_and_b32_e32 v101, 0xffff0000, v101
	v_lshlrev_b32_e32 v102, 16, v103
	v_and_b32_e32 v103, 0xffff0000, v103
	v_pk_add_f32 v[166:167], v[166:167], v[168:169]
	s_waitcnt vmcnt(37)
	v_lshlrev_b32_e32 v168, 16, v104
	v_and_b32_e32 v169, 0xffff0000, v104
	s_waitcnt vmcnt(36)
	v_lshlrev_b32_e32 v170, 16, v106
	v_and_b32_e32 v171, 0xffff0000, v106
	v_pk_add_f32 v[100:101], v[100:101], v[102:103]
	v_lshlrev_b32_e32 v102, 16, v105
	v_and_b32_e32 v103, 0xffff0000, v105
	v_lshlrev_b32_e32 v104, 16, v107
	v_and_b32_e32 v105, 0xffff0000, v107
	v_pk_add_f32 v[168:169], v[168:169], v[170:171]
	v_pk_add_f32 v[102:103], v[102:103], v[104:105]
	v_pk_add_f32 v[166:167], v[166:167], v[168:169]
	v_pk_add_f32 v[168:169], v[100:101], v[102:103]
	s_waitcnt vmcnt(34)
	v_lshlrev_b32_e32 v100, 16, v108
	v_and_b32_e32 v101, 0xffff0000, v108
	s_waitcnt vmcnt(33)
	v_lshlrev_b32_e32 v102, 16, v110
	v_and_b32_e32 v103, 0xffff0000, v110
	v_pk_add_f32 v[100:101], v[100:101], v[102:103]
	s_waitcnt vmcnt(32)
	v_lshlrev_b32_e32 v102, 16, v112
	v_and_b32_e32 v103, 0xffff0000, v112
	s_waitcnt vmcnt(31)
	v_lshlrev_b32_e32 v104, 16, v114
	v_and_b32_e32 v105, 0xffff0000, v114
	v_pk_add_f32 v[102:103], v[102:103], v[104:105]
	v_lshlrev_b32_e32 v104, 16, v115
	v_pk_add_f32 v[170:171], v[100:101], v[102:103]
	v_lshlrev_b32_e32 v100, 16, v109
	v_and_b32_e32 v101, 0xffff0000, v109
	v_lshlrev_b32_e32 v102, 16, v111
	v_and_b32_e32 v103, 0xffff0000, v111
	v_pk_add_f32 v[100:101], v[100:101], v[102:103]
	v_lshlrev_b32_e32 v102, 16, v113
	v_and_b32_e32 v103, 0xffff0000, v113
	v_and_b32_e32 v105, 0xffff0000, v115
	v_pk_add_f32 v[102:103], v[102:103], v[104:105]
	s_waitcnt vmcnt(26)
	v_lshlrev_b32_e32 v104, 16, v122
	v_pk_add_f32 v[172:173], v[100:101], v[102:103]
	v_lshlrev_b32_e32 v100, 16, v116
	v_and_b32_e32 v101, 0xffff0000, v116
	v_lshlrev_b32_e32 v102, 16, v118
	v_and_b32_e32 v103, 0xffff0000, v118
	v_pk_add_f32 v[100:101], v[100:101], v[102:103]
	v_lshlrev_b32_e32 v102, 16, v120
	v_and_b32_e32 v103, 0xffff0000, v120
	v_and_b32_e32 v105, 0xffff0000, v122
	v_pk_add_f32 v[102:103], v[102:103], v[104:105]
	v_lshlrev_b32_e32 v104, 16, v123
	v_pk_add_f32 v[174:175], v[100:101], v[102:103]
	v_lshlrev_b32_e32 v100, 16, v117
	v_and_b32_e32 v101, 0xffff0000, v117
	v_lshlrev_b32_e32 v102, 16, v119
	v_and_b32_e32 v103, 0xffff0000, v119
	v_pk_add_f32 v[100:101], v[100:101], v[102:103]
	v_lshlrev_b32_e32 v102, 16, v121
	v_and_b32_e32 v103, 0xffff0000, v121
	v_and_b32_e32 v105, 0xffff0000, v123
	v_pk_add_f32 v[102:103], v[102:103], v[104:105]
	s_waitcnt vmcnt(21)
	v_lshlrev_b32_e32 v104, 16, v182
	v_pk_add_f32 v[176:177], v[100:101], v[102:103]
	v_mov_b32_e32 v102, v175
	v_mov_b32_e32 v103, v177
	v_mov_b32_e32 v100, v174
	v_mov_b32_e32 v101, v176
	v_pk_mul_f32 v[102:103], v[102:103], v[102:103]
	v_and_b32_e32 v105, 0xffff0000, v182
	v_pk_fma_f32 v[100:101], v[100:101], v[100:101], v[102:103]
	v_lshlrev_b32_e32 v102, 16, v126
	v_pk_add_f32 v[192:193], v[100:101], v[100:101] op_sel:[0,1] op_sel_hi:[1,0]
	v_lshlrev_b32_e32 v100, 16, v124
	v_and_b32_e32 v101, 0xffff0000, v124
	v_and_b32_e32 v103, 0xffff0000, v126
	v_pk_add_f32 v[100:101], v[100:101], v[102:103]
	v_lshlrev_b32_e32 v102, 16, v180
	v_and_b32_e32 v103, 0xffff0000, v180
	v_pk_add_f32 v[102:103], v[102:103], v[104:105]
	v_lshlrev_b32_e32 v104, 16, v183
	v_pk_add_f32 v[178:179], v[100:101], v[102:103]
	v_lshlrev_b32_e32 v100, 16, v125
	v_and_b32_e32 v101, 0xffff0000, v125
	v_lshlrev_b32_e32 v102, 16, v127
	v_and_b32_e32 v103, 0xffff0000, v127
	v_pk_add_f32 v[100:101], v[100:101], v[102:103]
	v_lshlrev_b32_e32 v102, 16, v181
	v_and_b32_e32 v103, 0xffff0000, v181
	v_and_b32_e32 v105, 0xffff0000, v183
	v_pk_add_f32 v[102:103], v[102:103], v[104:105]
	s_waitcnt vmcnt(16)
	v_lshlrev_b32_e32 v104, 16, v96
	v_pk_add_f32 v[180:181], v[100:101], v[102:103]
	v_mul_f32_e32 v100, v179, v179
	v_pk_fma_f32 v[198:199], v[178:179], v[178:179], v[100:101] op_sel_hi:[1,1,0]
	v_mul_f32_e32 v100, v181, v181
	v_pk_fma_f32 v[200:201], v[180:181], v[180:181], v[100:101] op_sel_hi:[1,1,0]
	v_lshlrev_b32_e32 v100, 16, v184
	v_and_b32_e32 v101, 0xffff0000, v184
	v_lshlrev_b32_e32 v102, 16, v186
	v_and_b32_e32 v103, 0xffff0000, v186
	v_pk_add_f32 v[100:101], v[100:101], v[102:103]
	v_lshlrev_b32_e32 v102, 16, v98
	v_and_b32_e32 v103, 0xffff0000, v98
	v_and_b32_e32 v105, 0xffff0000, v96
	v_pk_add_f32 v[102:103], v[102:103], v[104:105]
	v_lshlrev_b32_e32 v98, 16, v99
	v_pk_add_f32 v[182:183], v[100:101], v[102:103]
	v_lshlrev_b32_e32 v100, 16, v185
	v_and_b32_e32 v101, 0xffff0000, v185
	v_lshlrev_b32_e32 v102, 16, v187
	v_and_b32_e32 v103, 0xffff0000, v187
	v_and_b32_e32 v99, 0xffff0000, v99
	v_lshlrev_b32_e32 v96, 16, v97
	v_and_b32_e32 v97, 0xffff0000, v97
	v_pk_add_f32 v[100:101], v[100:101], v[102:103]
	v_pk_add_f32 v[96:97], v[98:99], v[96:97]
	s_waitcnt vmcnt(13)
	v_lshlrev_b32_e32 v98, 16, v94
	v_pk_add_f32 v[184:185], v[100:101], v[96:97]
	v_lshlrev_b32_e32 v96, 16, v92
	v_and_b32_e32 v97, 0xffff0000, v92
	v_and_b32_e32 v99, 0xffff0000, v94
	v_pk_add_f32 v[96:97], v[96:97], v[98:99]
	s_waitcnt vmcnt(12)
	v_lshlrev_b32_e32 v98, 16, v90
	v_and_b32_e32 v99, 0xffff0000, v90
	s_waitcnt vmcnt(11)
	v_lshlrev_b32_e32 v100, 16, v88
	v_and_b32_e32 v101, 0xffff0000, v88
	v_lshlrev_b32_e32 v92, 16, v93
	v_and_b32_e32 v93, 0xffff0000, v93
	v_lshlrev_b32_e32 v94, 16, v95
	v_and_b32_e32 v95, 0xffff0000, v95
	v_lshlrev_b32_e32 v90, 16, v91
	v_and_b32_e32 v91, 0xffff0000, v91
	v_lshlrev_b32_e32 v88, 16, v89
	v_and_b32_e32 v89, 0xffff0000, v89
	v_pk_add_f32 v[98:99], v[98:99], v[100:101]
	v_pk_add_f32 v[92:93], v[92:93], v[94:95]
	v_pk_add_f32 v[88:89], v[90:91], v[88:89]
	v_pk_add_f32 v[186:187], v[96:97], v[98:99]
	v_pk_add_f32 v[188:189], v[92:93], v[88:89]
	v_mov_b32_e32 v90, v187
	v_mov_b32_e32 v91, v189
	v_mov_b32_e32 v88, v186
	v_mov_b32_e32 v89, v188
	v_pk_mul_f32 v[90:91], v[90:91], v[90:91]
	s_waitcnt vmcnt(6)
	v_lshlrev_b32_e32 v92, 16, v80
	v_pk_fma_f32 v[88:89], v[88:89], v[88:89], v[90:91]
	v_lshlrev_b32_e32 v90, 16, v86
	v_pk_add_f32 v[206:207], v[88:89], v[88:89] op_sel:[0,1] op_sel_hi:[1,0]
	v_lshlrev_b32_e32 v88, 16, v84
	v_and_b32_e32 v89, 0xffff0000, v84
	v_and_b32_e32 v91, 0xffff0000, v86
	v_pk_add_f32 v[88:89], v[88:89], v[90:91]
	v_lshlrev_b32_e32 v90, 16, v82
	v_and_b32_e32 v91, 0xffff0000, v82
	v_and_b32_e32 v93, 0xffff0000, v80
	v_pk_add_f32 v[90:91], v[90:91], v[92:93]
	v_lshlrev_b32_e32 v84, 16, v85
	v_and_b32_e32 v85, 0xffff0000, v85
	v_lshlrev_b32_e32 v86, 16, v87
	v_and_b32_e32 v87, 0xffff0000, v87
	v_lshlrev_b32_e32 v82, 16, v83
	v_and_b32_e32 v83, 0xffff0000, v83
	v_lshlrev_b32_e32 v80, 16, v81
	v_and_b32_e32 v81, 0xffff0000, v81
	v_pk_add_f32 v[190:191], v[88:89], v[90:91]
	v_pk_add_f32 v[84:85], v[84:85], v[86:87]
	v_pk_add_f32 v[80:81], v[82:83], v[80:81]
	s_waitcnt vmcnt(3)
	v_lshlrev_b32_e32 v82, 16, v78
	v_pk_add_f32 v[194:195], v[84:85], v[80:81]
	v_mul_f32_e32 v80, v191, v191
	v_pk_fma_f32 v[208:209], v[190:191], v[190:191], v[80:81] op_sel_hi:[1,1,0]
	v_mul_f32_e32 v80, v195, v195
	v_pk_fma_f32 v[210:211], v[194:195], v[194:195], v[80:81] op_sel_hi:[1,1,0]
	v_lshlrev_b32_e32 v80, 16, v76
	v_and_b32_e32 v81, 0xffff0000, v76
	v_and_b32_e32 v83, 0xffff0000, v78
	v_pk_add_f32 v[80:81], v[80:81], v[82:83]
	s_waitcnt vmcnt(2)
	v_lshlrev_b32_e32 v82, 16, v74
	v_and_b32_e32 v83, 0xffff0000, v74
	s_waitcnt vmcnt(1)
	v_lshlrev_b32_e32 v84, 16, v72
	v_and_b32_e32 v85, 0xffff0000, v72
	v_lshlrev_b32_e32 v76, 16, v77
	v_and_b32_e32 v77, 0xffff0000, v77
	v_lshlrev_b32_e32 v78, 16, v79
	v_and_b32_e32 v79, 0xffff0000, v79
	v_lshlrev_b32_e32 v74, 16, v75
	v_and_b32_e32 v75, 0xffff0000, v75
	v_lshlrev_b32_e32 v72, 16, v73
	v_and_b32_e32 v73, 0xffff0000, v73
	v_pk_add_f32 v[82:83], v[82:83], v[84:85]
	v_pk_add_f32 v[76:77], v[76:77], v[78:79]
	v_pk_add_f32 v[72:73], v[74:75], v[72:73]
	v_pk_add_f32 v[196:197], v[80:81], v[82:83]
	v_pk_add_f32 v[212:213], v[76:77], v[72:73]
	v_pk_mul_f32 v[202:203], v[182:183], v[182:183]
	v_pk_mul_f32 v[204:205], v[184:185], v[184:185]
	v_pk_mul_f32 v[214:215], v[196:197], v[196:197]
	v_pk_mul_f32 v[216:217], v[212:213], v[212:213]
	v_lshl_add_u64 v[218:219], v[64:65], 0, s[54:55]
	v_lshl_add_u64 v[64:65], v[64:65], 0, s[56:57]
	v_lshl_add_u64 v[72:73], v[218:219], 0, v[134:135]
	v_lshl_add_u64 v[74:75], v[64:65], 0, v[134:135]
	global_load_dwordx4 v[120:123], v[72:73], off
	global_load_dwordx4 v[124:127], v[74:75], off
	v_lshl_add_u64 v[72:73], v[218:219], 0, v[66:67]
	v_lshl_add_u64 v[66:67], v[64:65], 0, v[66:67]
	global_load_dwordx4 v[112:115], v[72:73], off
	global_load_dwordx4 v[116:119], v[66:67], off
	v_lshl_add_u64 v[66:67], v[218:219], 0, v[68:69]
	v_lshl_add_u64 v[68:69], v[64:65], 0, v[68:69]
	global_load_dwordx4 v[104:107], v[66:67], off
	global_load_dwordx4 v[108:111], v[68:69], off
	v_lshl_add_u64 v[66:67], v[218:219], 0, v[70:71]
	v_lshl_add_u64 v[68:69], v[64:65], 0, v[70:71]
	global_load_dwordx4 v[96:99], v[66:67], off
	global_load_dwordx4 v[100:103], v[68:69], off
	v_lshl_add_u64 v[66:67], v[218:219], 0, v[162:163]
	v_lshl_add_u64 v[68:69], v[64:65], 0, v[162:163]
	global_load_dwordx4 v[88:91], v[66:67], off
	global_load_dwordx4 v[92:95], v[68:69], off
	v_lshl_add_u64 v[66:67], v[218:219], 0, v[160:161]
	v_lshl_add_u64 v[68:69], v[64:65], 0, v[160:161]
	global_load_dwordx4 v[80:83], v[66:67], off
	global_load_dwordx4 v[84:87], v[68:69], off
	v_lshl_add_u64 v[66:67], v[218:219], 0, v[158:159]
	v_lshl_add_u64 v[68:69], v[64:65], 0, v[158:159]
	global_load_dwordx4 v[72:75], v[66:67], off
	global_load_dwordx4 v[76:79], v[68:69], off
	v_lshl_add_u64 v[66:67], v[218:219], 0, v[156:157]
	v_lshl_add_u64 v[68:69], v[64:65], 0, v[156:157]
	global_load_dwordx4 v[64:67], v[66:67], off
	s_nop 0
	global_load_dwordx4 v[68:71], v[68:69], off
	v_mov_b32_e32 v222, v169
	v_mov_b32_e32 v223, v173
	v_mov_b32_e32 v218, v167
	v_mov_b32_e32 v219, v171
	v_mov_b32_e32 v220, v168
	v_mov_b32_e32 v221, v172
	v_pk_mul_f32 v[222:223], v[222:223], v[222:223]
	v_pk_mul_f32 v[218:219], v[218:219], v[218:219]
	v_pk_fma_f32 v[220:221], v[220:221], v[220:221], v[222:223]
	v_mov_b32_e32 v222, v166
	v_mov_b32_e32 v223, v170
	v_pk_fma_f32 v[218:219], v[222:223], v[222:223], v[218:219]
	v_mov_b32_e32 v199, v204
	v_pk_add_f32 v[218:219], v[218:219], v[220:221]
	v_mov_b32_e32 v201, v205
	v_pk_add_f32 v[218:219], v[218:219], v[218:219] op_sel:[0,1] op_sel_hi:[1,0]
	v_mov_b32_e32 v193, v203
	v_mov_b32_e32 v219, v202
	v_pk_add_f32 v[198:199], v[198:199], v[200:201]
	v_pk_add_f32 v[192:193], v[218:219], v[192:193]
	v_mov_b32_e32 v209, v216
	v_pk_add_f32 v[192:193], v[192:193], v[198:199]
	v_mov_b32_e32 v211, v217
	v_pk_add_f32 v[192:193], v[192:193], v[192:193] op_sel:[0,1] op_sel_hi:[1,0]
	v_mov_b32_e32 v207, v215
	v_mov_b32_e32 v193, v214
	v_pk_add_f32 v[198:199], v[208:209], v[210:211]
	v_pk_add_f32 v[192:193], v[192:193], v[206:207]
	s_nop 0
	v_pk_add_f32 v[192:193], v[192:193], v[198:199]
	s_nop 0
	v_add_f32_e32 v147, v192, v193
	ds_bpermute_b32 v149, v129, v147
	v_lshl_add_u64 v[164:165], s[48:49], 0, v[164:165]
	v_lshl_add_u64 v[192:193], v[164:165], 0, v[134:135]
	v_lshl_add_u64 v[162:163], v[164:165], 0, v[162:163]
	s_waitcnt lgkmcnt(0)
	v_add_f32_e32 v147, v147, v149
	ds_bpermute_b32 v149, v133, v147
	s_waitcnt lgkmcnt(0)
	v_add_f32_e32 v147, v147, v149
	ds_bpermute_b32 v149, v137, v147
	s_waitcnt lgkmcnt(0)
	v_add_f32_e32 v147, v147, v149
	ds_bpermute_b32 v149, v139, v147
	s_waitcnt lgkmcnt(0)
	v_add_f32_e32 v147, v147, v149
	ds_bpermute_b32 v149, v141, v147
	s_waitcnt lgkmcnt(0)
	v_add_f32_e32 v147, v147, v149
	ds_bpermute_b32 v149, v143, v147
	s_waitcnt lgkmcnt(0)
	v_add_f32_e32 v147, v147, v149
	v_fmamk_f32 v147, v147, 0x3a000000, v145
	v_mul_f32_e32 v149, 0x4b800000, v147
	v_cmp_gt_f32_e32 vcc, s59, v147
	s_nop 1
	v_cndmask_b32_e32 v147, v147, v149, vcc
	v_rsq_f32_e32 v147, v147
	s_nop 0
	v_mul_f32_e32 v134, 0x45800000, v147
	v_cndmask_b32_e32 v134, v147, v134, vcc
	v_pk_mul_f32 v[166:167], v[166:167], v[134:135] op_sel_hi:[1,0]
	v_pk_mul_f32 v[168:169], v[168:169], v[134:135] op_sel_hi:[1,0]
	v_pk_mul_f32 v[186:187], v[186:187], v[134:135] op_sel_hi:[1,0]
	v_pk_fma_f32 v[24:25], v[32:33], v[166:167], v[24:25]
	v_pk_mul_f32 v[32:33], v[188:189], v[134:135] op_sel_hi:[1,0]
	v_pk_mul_f32 v[170:171], v[170:171], v[134:135] op_sel_hi:[1,0]
	v_pk_mul_f32 v[172:173], v[172:173], v[134:135] op_sel_hi:[1,0]
	v_pk_mul_f32 v[174:175], v[174:175], v[134:135] op_sel_hi:[1,0]
	v_pk_mul_f32 v[176:177], v[176:177], v[134:135] op_sel_hi:[1,0]
	v_pk_mul_f32 v[178:179], v[178:179], v[134:135] op_sel_hi:[1,0]
	v_pk_mul_f32 v[180:181], v[180:181], v[134:135] op_sel_hi:[1,0]
	v_pk_mul_f32 v[182:183], v[182:183], v[134:135] op_sel_hi:[1,0]
	v_pk_mul_f32 v[184:185], v[184:185], v[134:135] op_sel_hi:[1,0]
	v_pk_fma_f32 v[26:27], v[34:35], v[168:169], v[26:27]
	v_pk_fma_f32 v[10:11], v[54:55], v[32:33], v[10:11]
	v_pk_fma_f32 v[8:9], v[52:53], v[186:187], v[8:9]
	v_lshl_add_u64 v[32:33], v[164:165], 0, v[160:161]
	v_pk_fma_f32 v[22:23], v[38:39], v[172:173], v[22:23]
	v_pk_fma_f32 v[20:21], v[36:37], v[170:171], v[20:21]
	v_pk_fma_f32 v[18:19], v[42:43], v[176:177], v[18:19]
	v_pk_fma_f32 v[16:17], v[40:41], v[174:175], v[16:17]
	v_pk_fma_f32 v[14:15], v[46:47], v[180:181], v[14:15]
	v_pk_fma_f32 v[12:13], v[44:45], v[178:179], v[12:13]
	v_pk_fma_f32 v[30:31], v[50:51], v[184:185], v[30:31]
	v_pk_fma_f32 v[28:29], v[48:49], v[182:183], v[28:29]
	global_store_dwordx4 v[192:193], v[24:27], off
	global_store_dwordx4 v[192:193], v[20:23], off offset:1024
	global_store_dwordx4 v[192:193], v[16:19], off offset:2048
	global_store_dwordx4 v[192:193], v[12:15], off offset:3072
	global_store_dwordx4 v[162:163], v[28:31], off
	global_store_dwordx4 v[32:33], v[8:11], off
	v_pk_mul_f32 v[32:33], v[190:191], v[134:135] op_sel_hi:[1,0]
	v_pk_mul_f32 v[34:35], v[194:195], v[134:135] op_sel_hi:[1,0]
	v_pk_fma_f32 v[4:5], v[60:61], v[32:33], v[4:5]
	v_pk_fma_f32 v[6:7], v[62:63], v[34:35], v[6:7]
	v_lshl_add_u64 v[32:33], v[164:165], 0, v[158:159]
	global_store_dwordx4 v[32:33], v[4:7], off
	v_pk_mul_f32 v[32:33], v[196:197], v[134:135] op_sel_hi:[1,0]
	v_pk_mul_f32 v[34:35], v[212:213], v[134:135] op_sel_hi:[1,0]
	s_waitcnt vmcnt(23)
	v_pk_fma_f32 v[0:1], v[56:57], v[32:33], v[0:1]
	v_pk_fma_f32 v[2:3], v[58:59], v[34:35], v[2:3]
	v_lshl_add_u64 v[32:33], v[164:165], 0, v[156:157]
	global_store_dwordx4 v[32:33], v[0:3], off
	v_mov_b32_e32 v34, v25
	v_mov_b32_e32 v35, v21
	v_mov_b32_e32 v32, v24
	v_mov_b32_e32 v33, v20
	v_pk_mul_f32 v[34:35], v[34:35], v[34:35]
	v_mov_b32_e32 v36, v27
	v_mov_b32_e32 v37, v23
	v_pk_fma_f32 v[32:33], v[32:33], v[32:33], v[34:35]
	v_mov_b32_e32 v34, v26
	v_mov_b32_e32 v35, v22
	v_pk_mul_f32 v[36:37], v[36:37], v[36:37]
	v_readfirstlane_b32 s83, v237
	s_lshl_b32 s83, s83, 1
	s_add_u32 s83, s83, s86
	s_add_u32 s83, s83, s94
	s_lshl_b32 s83, s83, 3
	s_sub_u32 s84, s83, s82
	s_mov_b32 s82, s83
	s_mov_b32 s85, 0
	s_mov_b64 s[6:7], s[84:85]
	s_lshl_b64 s[28:29], s[84:85], 13
	v_lshl_add_u64 v[130:131], v[130:131], 0, s[6:7]
	v_pk_fma_f32 v[34:35], v[34:35], v[34:35], v[36:37]
	v_pk_mul_f32 v[36:37], v[16:17], v[16:17]
	v_pk_add_f32 v[32:33], v[32:33], v[34:35]
	v_pk_mul_f32 v[34:35], v[18:19], v[18:19]
	v_pk_add_f32 v[32:33], v[32:33], v[32:33] op_sel_hi:[0,1]
	v_pk_mov_b32 v[38:39], v[36:37], v[34:35] op_sel:[1,0]
	v_mov_b32_e32 v37, v35
	v_mul_f32_e32 v32, v12, v12
	v_pk_add_f32 v[34:35], v[38:39], v[36:37]
	v_pk_fma_f32 v[36:37], v[12:13], v[12:13], v[32:33] op_sel_hi:[1,1,0]
	v_mul_f32_e32 v32, v14, v14
	v_pk_add_f32 v[34:35], v[34:35], v[34:35] op_sel_hi:[0,1]
	v_pk_fma_f32 v[38:39], v[14:15], v[14:15], v[32:33] op_sel_hi:[1,1,0]
	v_mul_f32_e32 v36, v28, v28
	v_mul_f32_e32 v38, v29, v29
	v_mul_f32_e32 v34, v30, v30
	v_mul_f32_e32 v32, v31, v31
	v_pk_add_f32 v[36:37], v[36:37], v[38:39]
	v_pk_add_f32 v[32:33], v[34:35], v[32:33]
	v_pk_mul_f32 v[34:35], v[10:11], v[10:11]
	v_pk_add_f32 v[32:33], v[36:37], v[32:33]
	v_pk_mul_f32 v[36:37], v[8:9], v[8:9]
	v_pk_add_f32 v[32:33], v[32:33], v[32:33] op_sel_hi:[0,1]
	v_pk_mov_b32 v[38:39], v[36:37], v[34:35] op_sel:[1,0]
	v_mov_b32_e32 v37, v35
	v_mul_f32_e32 v32, v4, v4
	v_pk_add_f32 v[34:35], v[38:39], v[36:37]
	v_pk_fma_f32 v[36:37], v[4:5], v[4:5], v[32:33] op_sel_hi:[1,1,0]
	v_mul_f32_e32 v32, v6, v6
	v_pk_add_f32 v[34:35], v[34:35], v[34:35] op_sel_hi:[0,1]
	v_pk_fma_f32 v[38:39], v[6:7], v[6:7], v[32:33] op_sel_hi:[1,1,0]
	v_mul_f32_e32 v36, v0, v0
	v_mul_f32_e32 v38, v1, v1
	v_mul_f32_e32 v34, v2, v2
	v_mul_f32_e32 v32, v3, v3
	v_pk_add_f32 v[36:37], v[36:37], v[38:39]
	v_pk_add_f32 v[32:33], v[34:35], v[32:33]
	v_lshlrev_b64 v[34:35], 12, v[154:155]
	v_pk_add_f32 v[32:33], v[36:37], v[32:33]
	v_lshl_add_u64 v[152:153], v[152:153], 0, s[28:29]
	v_add_f32_e32 v32, v32, v33
	ds_bpermute_b32 v33, v129, v32
	s_waitcnt lgkmcnt(0)
	v_add_f32_e32 v32, v32, v33
	ds_bpermute_b32 v33, v133, v32
	s_waitcnt lgkmcnt(0)
	v_add_f32_e32 v32, v32, v33
	ds_bpermute_b32 v33, v137, v32
	s_waitcnt lgkmcnt(0)
	v_add_f32_e32 v32, v32, v33
	ds_bpermute_b32 v33, v139, v32
	s_waitcnt lgkmcnt(0)
	v_add_f32_e32 v32, v32, v33
	ds_bpermute_b32 v33, v141, v32
	s_waitcnt lgkmcnt(0)
	v_add_f32_e32 v32, v32, v33
	ds_bpermute_b32 v33, v143, v32
	s_waitcnt lgkmcnt(0)
	v_add_f32_e32 v32, v32, v33
	v_fmamk_f32 v32, v32, 0x3a000000, v145
	v_mul_f32_e32 v33, 0x4b800000, v32
	v_cmp_gt_f32_e32 vcc, s59, v32
	s_nop 1
	v_cndmask_b32_e32 v32, v32, v33, vcc
	v_rsq_f32_e32 v32, v32
	s_nop 0
	v_mul_f32_e32 v33, 0x45800000, v32
	v_cndmask_b32_e32 v32, v32, v33, vcc
	v_pk_mul_f32 v[24:25], v[24:25], v[32:33] op_sel_hi:[1,0]
	v_pk_mul_f32 v[26:27], v[26:27], v[32:33] op_sel_hi:[1,0]
	v_pk_mul_f32 v[12:13], v[12:13], v[32:33] op_sel_hi:[1,0]
	v_pk_mul_f32 v[14:15], v[14:15], v[32:33] op_sel_hi:[1,0]
	s_waitcnt vmcnt(22)
	v_pk_fma_f32 v[26:27], v[122:123], v[26:27], v[126:127]
	v_pk_fma_f32 v[24:25], v[120:121], v[24:25], v[124:125]
	s_waitcnt vmcnt(16)
	v_pk_fma_f32 v[14:15], v[98:99], v[14:15], v[102:103]
	v_pk_fma_f32 v[12:13], v[96:97], v[12:13], v[100:101]
	v_cvt_pk_bf16_f32 v24, v24, v25
	v_cvt_pk_bf16_f32 v25, v26, v27
	v_lshl_add_u64 v[26:27], v[150:151], 0, v[34:35]
	v_cvt_pk_bf16_f32 v12, v12, v13
	v_cvt_pk_bf16_f32 v13, v14, v15
	v_pk_mul_f32 v[20:21], v[20:21], v[32:33] op_sel_hi:[1,0]
	v_pk_mul_f32 v[22:23], v[22:23], v[32:33] op_sel_hi:[1,0]
	v_pk_mul_f32 v[16:17], v[16:17], v[32:33] op_sel_hi:[1,0]
	v_pk_mul_f32 v[18:19], v[18:19], v[32:33] op_sel_hi:[1,0]
	global_store_dwordx2 v[26:27], v[12:13], off offset:1536
	v_pk_mul_f32 v[12:13], v[28:29], v[32:33] op_sel_hi:[1,0]
	v_pk_mul_f32 v[14:15], v[30:31], v[32:33] op_sel_hi:[1,0]
	v_pk_mul_f32 v[8:9], v[8:9], v[32:33] op_sel_hi:[1,0]
	v_pk_mul_f32 v[10:11], v[10:11], v[32:33] op_sel_hi:[1,0]
	v_pk_mul_f32 v[4:5], v[4:5], v[32:33] op_sel_hi:[1,0]
	v_pk_mul_f32 v[6:7], v[6:7], v[32:33] op_sel_hi:[1,0]
	v_pk_mul_f32 v[0:1], v[0:1], v[32:33] op_sel_hi:[1,0]
	v_pk_mul_f32 v[2:3], v[2:3], v[32:33] op_sel_hi:[1,0]
	v_pk_fma_f32 v[22:23], v[114:115], v[22:23], v[118:119]
	v_pk_fma_f32 v[20:21], v[112:113], v[20:21], v[116:117]
	v_pk_fma_f32 v[18:19], v[106:107], v[18:19], v[110:111]
	v_pk_fma_f32 v[16:17], v[104:105], v[16:17], v[108:109]
	s_waitcnt vmcnt(15)
	v_pk_fma_f32 v[14:15], v[90:91], v[14:15], v[94:95]
	v_pk_fma_f32 v[12:13], v[88:89], v[12:13], v[92:93]
	s_waitcnt vmcnt(13)
	v_pk_fma_f32 v[10:11], v[82:83], v[10:11], v[86:87]
	v_pk_fma_f32 v[8:9], v[80:81], v[8:9], v[84:85]
	s_waitcnt vmcnt(11)
	v_pk_fma_f32 v[6:7], v[74:75], v[6:7], v[78:79]
	v_pk_fma_f32 v[4:5], v[72:73], v[4:5], v[76:77]
	s_waitcnt vmcnt(9)
	v_pk_fma_f32 v[2:3], v[66:67], v[2:3], v[70:71]
	v_pk_fma_f32 v[0:1], v[64:65], v[0:1], v[68:69]
	v_cmp_lt_i32_e32 vcc, s60, v130
	v_cvt_pk_bf16_f32 v20, v20, v21
	v_cvt_pk_bf16_f32 v21, v22, v23
	v_cvt_pk_bf16_f32 v16, v16, v17
	v_cvt_pk_bf16_f32 v17, v18, v19
	v_cvt_pk_bf16_f32 v12, v12, v13
	v_cvt_pk_bf16_f32 v13, v14, v15
	v_cvt_pk_bf16_f32 v8, v8, v9
	v_cvt_pk_bf16_f32 v9, v10, v11
	v_cvt_pk_bf16_f32 v4, v4, v5
	v_cvt_pk_bf16_f32 v5, v6, v7
	v_cvt_pk_bf16_f32 v0, v0, v1
	v_cvt_pk_bf16_f32 v1, v2, v3
	s_or_b64 s[30:31], vcc, s[30:31]
	global_store_dwordx2 v[26:27], v[24:25], off
	global_store_dwordx2 v[26:27], v[20:21], off offset:512
	global_store_dwordx2 v[26:27], v[16:17], off offset:1024
	global_store_dwordx2 v[26:27], v[12:13], off offset:2048
	global_store_dwordx2 v[26:27], v[8:9], off offset:2560
	global_store_dwordx2 v[26:27], v[4:5], off offset:3072
	global_store_dwordx2 v[26:27], v[0:1], off offset:3584
	s_andn2_b64 exec, exec, s[30:31]
	s_cbranch_execz .LBB0_742

.LBB0_1623:
	v_lshrrev_b32_e32 v0, 6, v128
	s_waitcnt vmcnt(0)
	v_lshl_add_u32 v130, s34, 3, v0
	v_lshlrev_b32_e32 v236, 8, v0
	v_add_u32_e32 v236, 0x1480, v236
	s_and_b32 s86, s34, 1
	s_lshl_b32 s83, s86, 11
	v_add_u32_e32 v236, s83, v236
	s_lshl_b32 s82, s34, 3
	s_movk_i32 s0, 0x2400
	v_cmp_gt_i32_e32 vcc, s0, v130
	s_and_saveexec_b64 s[0:1], vcc
	s_cbranch_execz .LBB0_1626
	v_mbcnt_lo_u32_b32 v1, -1, 0
	v_mbcnt_hi_u32_b32 v1, -1, v1
	v_and_b32_e32 v2, 64, v1
	v_add_u32_e32 v2, 64, v2
	v_xor_b32_e32 v3, 1, v1
	v_cmp_lt_i32_e32 vcc, v3, v2
	v_ashrrev_i32_e32 v131, 31, v130
	v_lshlrev_b64 v[16:17], 12, v[130:131]
	v_cndmask_b32_e32 v3, v1, v3, vcc
	v_lshlrev_b32_e32 v129, 2, v3
	v_xor_b32_e32 v3, 2, v1
	v_cmp_lt_i32_e32 vcc, v3, v2
	s_mov_b64 s[6:7], 0x1ce05e00
	s_lshl_b32 s2, s94, 3
	v_cndmask_b32_e32 v3, v1, v3, vcc
	v_lshlrev_b32_e32 v184, 2, v3
	v_xor_b32_e32 v3, 4, v1
	v_cmp_lt_i32_e32 vcc, v3, v2
	v_lshlrev_b32_e32 v0, 2, v128
	s_add_u32 s12, s50, 0xc604000
	v_cndmask_b32_e32 v3, v1, v3, vcc
	v_lshlrev_b32_e32 v185, 2, v3
	v_xor_b32_e32 v3, 8, v1
	v_cmp_lt_i32_e32 vcc, v3, v2
	v_and_b32_e32 v0, 0xfc, v0
	s_addc_u32 s13, s51, 0
	v_cndmask_b32_e32 v3, v1, v3, vcc
	v_lshlrev_b32_e32 v186, 2, v3
	v_xor_b32_e32 v3, 16, v1
	v_cmp_lt_i32_e32 vcc, v3, v2
	v_mov_b32_e32 v133, 0
	v_or_b32_e32 v4, 0x200, v0
	v_cndmask_b32_e32 v3, v1, v3, vcc
	v_lshlrev_b32_e32 v187, 2, v3
	v_xor_b32_e32 v3, 32, v1
	v_cmp_lt_i32_e32 vcc, v3, v2
	v_or_b32_e32 v2, 0x100, v0
	v_or_b32_e32 v6, 0x300, v0
	v_cndmask_b32_e32 v1, v1, v3, vcc
	v_lshlrev_b32_e32 v188, 2, v1
	v_and_b32_e32 v1, 63, v128
	v_lshl_or_b32 v16, v1, 3, v16
	v_lshl_add_u64 v[16:17], s[50:51], 0, v[16:17]
	v_lshl_add_u64 v[134:135], v[16:17], 0, s[6:7]
	v_lshlrev_b64 v[16:17], 13, v[130:131]
	v_lshl_or_b32 v16, v1, 4, v16
	v_or_b32_e32 v8, 0x400, v0
	v_or_b32_e32 v10, 0x500, v0
	v_or_b32_e32 v12, 0x600, v0
	v_or_b32_e32 v14, 0x700, v0
	s_ashr_i32 s3, s2, 31
	v_lshl_add_u64 v[16:17], s[48:49], 0, v[16:17]
	s_mov_b64 s[8:9], 0x1000
	s_lshl_b64 s[6:7], s[2:3], 12
	v_lshl_add_u64 v[136:137], v[16:17], 0, s[8:9]
	s_lshl_b64 s[8:9], s[2:3], 13
	s_mov_b64 s[10:11], 0
	s_movk_i32 s3, 0x2000
	s_mov_b32 s18, 0x12000
	v_mov_b64_e32 v[138:139], s[12:13]
	s_mov_b64 s[12:13], 0xa000
	s_mov_b32 s19, 0xf3100000
	s_mov_b32 s20, 0xf5500000
	s_mov_b32 s21, 0xfdc00000
	v_lshlrev_b32_e32 v132, 2, v0
	v_lshlrev_b32_e32 v140, 2, v2
	v_mov_b32_e32 v141, v133
	v_lshlrev_b32_e32 v142, 2, v4
	v_mov_b32_e32 v143, v133
	v_lshlrev_b32_e32 v144, 2, v6
	v_mov_b32_e32 v145, v133
	v_lshlrev_b32_e32 v146, 2, v8
	v_mov_b32_e32 v147, v133
	v_lshlrev_b32_e32 v148, 2, v10
	v_mov_b32_e32 v149, v133
	v_lshlrev_b32_e32 v150, 2, v12
	v_mov_b32_e32 v151, v133
	v_lshlrev_b32_e32 v152, 2, v14
	v_mov_b32_e32 v153, v133
	s_mov_b64 s[14:15], 0xe000
	s_mov_b64 s[16:17], 0xc000
	v_mov_b32_e32 v131, 0x358637bd
	s_mov_b32 s22, 0x800000
	s_mov_b32 s23, 0xf0d00000
	s_movk_i32 s24, 0x23ff
.LBB0_1625:
	s_mov_b64 s[80:81], exec
	s_mov_b64 exec, 1
	v_mov_b32_e32 v237, 1
	global_atomic_add v237, v236, v237, s[50:51] sc0
	s_mov_b64 exec, s[80:81]
	global_load_dwordx4 v[28:31], v[136:137], off offset:-4096
	global_load_dwordx4 v[24:27], v[136:137], off offset:-3072
	global_load_dwordx4 v[20:23], v[136:137], off offset:-2048
	global_load_dwordx4 v[16:19], v[136:137], off offset:-1024
	global_load_dwordx4 v[12:15], v[136:137], off
	global_load_dwordx4 v[8:11], v[136:137], off offset:1024
	global_load_dwordx4 v[4:7], v[136:137], off offset:2048
	global_load_dwordx4 v[0:3], v[136:137], off offset:3072
	v_add_u32_e32 v33, 0xffffe000, v130
	v_lshrrev_b32_e32 v33, 3, v33
	v_ashrrev_i32_e32 v32, 12, v130
	v_add_u32_e32 v33, 2, v33
	v_cmp_gt_i32_e32 vcc, s3, v130
	s_nop 1
	v_cndmask_b32_e32 v32, v33, v32, vcc
	v_mad_i64_i32 v[64:65], s[26:27], v32, s18, v[138:139]
	v_add_co_u32_e32 v50, vcc, s19, v134
	v_lshl_add_u64 v[48:49], v[64:65], 0, s[12:13]
	s_nop 0
	v_addc_co_u32_e32 v51, vcc, -1, v135, vcc
	v_add_co_u32_e32 v60, vcc, s20, v134
	v_lshl_add_u64 v[40:41], v[48:49], 0, v[132:133]
	s_nop 0
	v_addc_co_u32_e32 v61, vcc, -1, v135, vcc
	v_add_co_u32_e32 v62, vcc, s21, v134
	v_lshl_add_u64 v[42:43], v[48:49], 0, v[140:141]
	v_lshl_add_u64 v[52:53], v[48:49], 0, v[142:143]
	v_lshl_add_u64 v[54:55], v[48:49], 0, v[144:145]
	v_addc_co_u32_e32 v63, vcc, -1, v135, vcc
	global_load_dwordx4 v[36:39], v[40:41], off
	global_load_dwordx4 v[32:35], v[42:43], off
	global_load_dwordx2 v[82:83], v[50:51], off offset:-3584
	global_load_dwordx2 v[84:85], v[50:51], off offset:-3072
	global_load_dwordx2 v[86:87], v[50:51], off offset:-2560
	global_load_dwordx2 v[88:89], v[50:51], off offset:-2048
	global_load_dwordx2 v[90:91], v[60:61], off offset:-3584
	global_load_dwordx2 v[92:93], v[60:61], off offset:-3072
	global_load_dwordx2 v[94:95], v[60:61], off offset:-2560
	global_load_dwordx2 v[96:97], v[60:61], off offset:-2048
	global_load_dwordx2 v[98:99], v[62:63], off offset:-3584
	global_load_dwordx2 v[100:101], v[62:63], off offset:-3072
	global_load_dwordx2 v[102:103], v[62:63], off offset:-2560
	global_load_dwordx2 v[104:105], v[62:63], off offset:-2048
	global_load_dwordx2 v[106:107], v[134:135], off offset:-3584
	global_load_dwordx2 v[108:109], v[134:135], off offset:-3072
	global_load_dwordx2 v[110:111], v[134:135], off offset:-2560
	global_load_dwordx2 v[112:113], v[134:135], off offset:-2048
	global_load_dwordx4 v[44:47], v[52:53], off
	global_load_dwordx4 v[40:43], v[54:55], off
	v_lshl_add_u64 v[52:53], v[48:49], 0, v[146:147]
	v_lshl_add_u64 v[54:55], v[48:49], 0, v[148:149]
	global_load_dwordx4 v[56:59], v[52:53], off
	s_nop 0
	global_load_dwordx4 v[52:55], v[54:55], off
	s_nop 0
	global_load_dwordx2 v[116:117], v[50:51], off offset:-1536
	global_load_dwordx2 v[118:119], v[50:51], off offset:-1024
	global_load_dwordx2 v[74:75], v[50:51], off offset:-512
	global_load_dwordx2 v[70:71], v[50:51], off
	global_load_dwordx2 v[120:121], v[60:61], off offset:-1536
	global_load_dwordx2 v[122:123], v[60:61], off offset:-1024
	global_load_dwordx2 v[80:81], v[60:61], off offset:-512
	global_load_dwordx2 v[72:73], v[60:61], off
	global_load_dwordx2 v[124:125], v[62:63], off offset:-1536
	global_load_dwordx2 v[126:127], v[62:63], off offset:-1024
	global_load_dwordx2 v[76:77], v[62:63], off offset:-512
	global_load_dwordx2 v[66:67], v[62:63], off
	global_load_dwordx2 v[172:173], v[134:135], off offset:-1536
	global_load_dwordx2 v[178:179], v[134:135], off offset:-1024
	global_load_dwordx2 v[78:79], v[134:135], off offset:-512
	global_load_dwordx2 v[68:69], v[134:135], off
	v_lshl_add_u64 v[114:115], v[48:49], 0, v[150:151]
	v_lshl_add_u64 v[48:49], v[48:49], 0, v[152:153]
	global_load_dwordx4 v[60:63], v[114:115], off
	s_nop 0
	global_load_dwordx4 v[48:51], v[48:49], off
	s_waitcnt vmcnt(37)
	v_lshlrev_b32_e32 v114, 16, v82
	v_and_b32_e32 v115, 0xffff0000, v82
	s_waitcnt vmcnt(33)
	v_lshlrev_b32_e32 v154, 16, v90
	v_and_b32_e32 v155, 0xffff0000, v90
	v_lshlrev_b32_e32 v82, 16, v83
	v_and_b32_e32 v83, 0xffff0000, v83
	v_lshlrev_b32_e32 v90, 16, v91
	v_and_b32_e32 v91, 0xffff0000, v91
	v_pk_add_f32 v[114:115], v[114:115], v[154:155]
	s_waitcnt vmcnt(29)
	v_lshlrev_b32_e32 v154, 16, v98
	v_and_b32_e32 v155, 0xffff0000, v98
	v_pk_add_f32 v[82:83], v[82:83], v[90:91]
	v_lshlrev_b32_e32 v90, 16, v99
	v_and_b32_e32 v91, 0xffff0000, v99
	s_waitcnt vmcnt(25)
	v_lshlrev_b32_e32 v98, 16, v107
	v_and_b32_e32 v99, 0xffff0000, v107
	v_lshlrev_b32_e32 v156, 16, v106
	v_and_b32_e32 v157, 0xffff0000, v106
	v_pk_add_f32 v[90:91], v[90:91], v[98:99]
	v_pk_add_f32 v[154:155], v[154:155], v[156:157]
	v_pk_add_f32 v[156:157], v[82:83], v[90:91]
	v_lshlrev_b32_e32 v82, 16, v84
	v_and_b32_e32 v83, 0xffff0000, v84
	v_lshlrev_b32_e32 v90, 16, v92
	v_and_b32_e32 v91, 0xffff0000, v92
	v_pk_add_f32 v[82:83], v[82:83], v[90:91]
	v_lshlrev_b32_e32 v90, 16, v100
	v_and_b32_e32 v91, 0xffff0000, v100
	s_waitcnt vmcnt(24)
	v_lshlrev_b32_e32 v98, 16, v108
	v_and_b32_e32 v99, 0xffff0000, v108
	v_pk_add_f32 v[90:91], v[90:91], v[98:99]
	v_lshlrev_b32_e32 v84, 16, v93
	v_pk_add_f32 v[158:159], v[82:83], v[90:91]
	v_lshlrev_b32_e32 v82, 16, v85
	v_and_b32_e32 v83, 0xffff0000, v85
	v_and_b32_e32 v85, 0xffff0000, v93
	v_pk_add_f32 v[82:83], v[82:83], v[84:85]
	v_lshlrev_b32_e32 v84, 16, v101
	v_and_b32_e32 v85, 0xffff0000, v101
	v_lshlrev_b32_e32 v90, 16, v109
	v_and_b32_e32 v91, 0xffff0000, v109
	v_pk_add_f32 v[84:85], v[84:85], v[90:91]
	s_waitcnt vmcnt(23)
	v_lshlrev_b32_e32 v90, 16, v110
	v_pk_add_f32 v[160:161], v[82:83], v[84:85]
	v_lshlrev_b32_e32 v82, 16, v86
	v_and_b32_e32 v83, 0xffff0000, v86
	v_lshlrev_b32_e32 v84, 16, v94
	v_and_b32_e32 v85, 0xffff0000, v94
	v_pk_add_f32 v[82:83], v[82:83], v[84:85]
	v_lshlrev_b32_e32 v84, 16, v102
	v_and_b32_e32 v85, 0xffff0000, v102
	v_and_b32_e32 v91, 0xffff0000, v110
	v_pk_add_f32 v[84:85], v[84:85], v[90:91]
	v_lshlrev_b32_e32 v86, 16, v111
	v_pk_add_f32 v[162:163], v[82:83], v[84:85]
	v_lshlrev_b32_e32 v82, 16, v87
	v_and_b32_e32 v83, 0xffff0000, v87
	v_lshlrev_b32_e32 v84, 16, v95
	v_and_b32_e32 v85, 0xffff0000, v95
	v_pk_add_f32 v[82:83], v[82:83], v[84:85]
	v_lshlrev_b32_e32 v84, 16, v103
	v_and_b32_e32 v85, 0xffff0000, v103
	v_and_b32_e32 v87, 0xffff0000, v111
	v_pk_add_f32 v[84:85], v[84:85], v[86:87]
	s_waitcnt vmcnt(22)
	v_lshlrev_b32_e32 v86, 16, v112
	v_pk_add_f32 v[164:165], v[82:83], v[84:85]
	v_mov_b32_e32 v84, v163
	v_mov_b32_e32 v85, v165
	v_mov_b32_e32 v82, v162
	v_mov_b32_e32 v83, v164
	v_pk_mul_f32 v[84:85], v[84:85], v[84:85]
	v_and_b32_e32 v87, 0xffff0000, v112
	v_pk_fma_f32 v[82:83], v[82:83], v[82:83], v[84:85]
	v_lshlrev_b32_e32 v84, 16, v96
	v_pk_add_f32 v[176:177], v[82:83], v[82:83] op_sel:[0,1] op_sel_hi:[1,0]
	v_lshlrev_b32_e32 v82, 16, v88
	v_and_b32_e32 v83, 0xffff0000, v88
	v_and_b32_e32 v85, 0xffff0000, v96
	v_pk_add_f32 v[82:83], v[82:83], v[84:85]
	v_lshlrev_b32_e32 v84, 16, v104
	v_and_b32_e32 v85, 0xffff0000, v104
	v_pk_add_f32 v[84:85], v[84:85], v[86:87]
	v_lshlrev_b32_e32 v86, 16, v113
	v_pk_add_f32 v[166:167], v[82:83], v[84:85]
	v_lshlrev_b32_e32 v82, 16, v89
	v_and_b32_e32 v83, 0xffff0000, v89
	v_lshlrev_b32_e32 v84, 16, v97
	v_and_b32_e32 v85, 0xffff0000, v97
	v_pk_add_f32 v[82:83], v[82:83], v[84:85]
	v_lshlrev_b32_e32 v84, 16, v105
	v_and_b32_e32 v85, 0xffff0000, v105
	v_and_b32_e32 v87, 0xffff0000, v113
	v_pk_add_f32 v[84:85], v[84:85], v[86:87]
	s_waitcnt vmcnt(5)
	v_lshlrev_b32_e32 v86, 16, v172
	v_pk_add_f32 v[168:169], v[82:83], v[84:85]
	v_mul_f32_e32 v82, v167, v167
	v_pk_fma_f32 v[190:191], v[166:167], v[166:167], v[82:83] op_sel_hi:[1,1,0]
	v_mul_f32_e32 v82, v169, v169
	v_pk_fma_f32 v[192:193], v[168:169], v[168:169], v[82:83] op_sel_hi:[1,1,0]
	v_lshlrev_b32_e32 v82, 16, v116
	v_and_b32_e32 v83, 0xffff0000, v116
	v_lshlrev_b32_e32 v84, 16, v120
	v_and_b32_e32 v85, 0xffff0000, v120
	v_pk_add_f32 v[82:83], v[82:83], v[84:85]
	v_lshlrev_b32_e32 v84, 16, v124
	v_and_b32_e32 v85, 0xffff0000, v124
	v_and_b32_e32 v87, 0xffff0000, v172
	v_pk_add_f32 v[84:85], v[84:85], v[86:87]
	v_lshlrev_b32_e32 v86, 16, v173
	v_pk_add_f32 v[170:171], v[82:83], v[84:85]
	v_lshlrev_b32_e32 v82, 16, v117
	v_and_b32_e32 v83, 0xffff0000, v117
	v_lshlrev_b32_e32 v84, 16, v121
	v_and_b32_e32 v85, 0xffff0000, v121
	v_pk_add_f32 v[82:83], v[82:83], v[84:85]
	v_lshlrev_b32_e32 v84, 16, v125
	v_and_b32_e32 v85, 0xffff0000, v125
	v_and_b32_e32 v87, 0xffff0000, v173
	v_pk_add_f32 v[84:85], v[84:85], v[86:87]
	s_waitcnt vmcnt(4)
	v_lshlrev_b32_e32 v86, 16, v178
	v_pk_add_f32 v[172:173], v[82:83], v[84:85]
	v_lshlrev_b32_e32 v82, 16, v118
	v_and_b32_e32 v83, 0xffff0000, v118
	v_lshlrev_b32_e32 v84, 16, v122
	v_and_b32_e32 v85, 0xffff0000, v122
	v_pk_add_f32 v[82:83], v[82:83], v[84:85]
	v_lshlrev_b32_e32 v84, 16, v126
	v_and_b32_e32 v85, 0xffff0000, v126
	v_and_b32_e32 v87, 0xffff0000, v178
	v_pk_add_f32 v[84:85], v[84:85], v[86:87]
	v_lshlrev_b32_e32 v86, 16, v179
	v_pk_add_f32 v[174:175], v[82:83], v[84:85]
	v_lshlrev_b32_e32 v82, 16, v119
	v_and_b32_e32 v83, 0xffff0000, v119
	v_lshlrev_b32_e32 v84, 16, v123
	v_and_b32_e32 v85, 0xffff0000, v123
	v_pk_add_f32 v[82:83], v[82:83], v[84:85]
	v_lshlrev_b32_e32 v84, 16, v127
	v_and_b32_e32 v85, 0xffff0000, v127
	v_and_b32_e32 v87, 0xffff0000, v179
	v_pk_add_f32 v[84:85], v[84:85], v[86:87]
	s_waitcnt vmcnt(3)
	v_lshlrev_b32_e32 v86, 16, v78
	v_pk_add_f32 v[178:179], v[82:83], v[84:85]
	v_mov_b32_e32 v84, v175
	v_mov_b32_e32 v85, v179
	v_mov_b32_e32 v82, v174
	v_mov_b32_e32 v83, v178
	v_pk_mul_f32 v[84:85], v[84:85], v[84:85]
	v_and_b32_e32 v87, 0xffff0000, v78
	v_pk_fma_f32 v[82:83], v[82:83], v[82:83], v[84:85]
	v_lshlrev_b32_e32 v84, 16, v80
	v_pk_add_f32 v[198:199], v[82:83], v[82:83] op_sel:[0,1] op_sel_hi:[1,0]
	v_lshlrev_b32_e32 v82, 16, v74
	v_and_b32_e32 v83, 0xffff0000, v74
	v_and_b32_e32 v85, 0xffff0000, v80
	v_pk_add_f32 v[82:83], v[82:83], v[84:85]
	v_lshlrev_b32_e32 v84, 16, v76
	v_and_b32_e32 v85, 0xffff0000, v76
	v_pk_add_f32 v[84:85], v[84:85], v[86:87]
	v_lshlrev_b32_e32 v74, 16, v75
	v_and_b32_e32 v75, 0xffff0000, v75
	v_lshlrev_b32_e32 v80, 16, v81
	v_and_b32_e32 v81, 0xffff0000, v81
	v_lshlrev_b32_e32 v76, 16, v77
	v_and_b32_e32 v77, 0xffff0000, v77
	v_lshlrev_b32_e32 v78, 16, v79
	v_and_b32_e32 v79, 0xffff0000, v79
	v_pk_add_f32 v[180:181], v[82:83], v[84:85]
	v_pk_add_f32 v[74:75], v[74:75], v[80:81]
	v_pk_add_f32 v[76:77], v[76:77], v[78:79]
	s_waitcnt vmcnt(2)
	v_lshlrev_b32_e32 v78, 16, v68
	v_pk_add_f32 v[182:183], v[74:75], v[76:77]
	v_mul_f32_e32 v74, v181, v181
	v_pk_fma_f32 v[200:201], v[180:181], v[180:181], v[74:75] op_sel_hi:[1,1,0]
	v_mul_f32_e32 v74, v183, v183
	v_pk_fma_f32 v[202:203], v[182:183], v[182:183], v[74:75] op_sel_hi:[1,1,0]
	v_lshlrev_b32_e32 v74, 16, v70
	v_and_b32_e32 v75, 0xffff0000, v70
	v_lshlrev_b32_e32 v76, 16, v72
	v_and_b32_e32 v77, 0xffff0000, v72
	v_pk_add_f32 v[74:75], v[74:75], v[76:77]
	v_lshlrev_b32_e32 v76, 16, v66
	v_and_b32_e32 v77, 0xffff0000, v66
	v_and_b32_e32 v79, 0xffff0000, v68
	v_lshlrev_b32_e32 v70, 16, v71
	v_and_b32_e32 v71, 0xffff0000, v71
	v_lshlrev_b32_e32 v72, 16, v73
	v_and_b32_e32 v73, 0xffff0000, v73
	v_lshlrev_b32_e32 v66, 16, v67
	v_and_b32_e32 v67, 0xffff0000, v67
	v_lshlrev_b32_e32 v68, 16, v69
	v_and_b32_e32 v69, 0xffff0000, v69
	v_pk_add_f32 v[76:77], v[76:77], v[78:79]
	v_pk_add_f32 v[70:71], v[70:71], v[72:73]
	v_pk_add_f32 v[66:67], v[66:67], v[68:69]
	v_pk_add_f32 v[204:205], v[74:75], v[76:77]
	v_pk_add_f32 v[206:207], v[70:71], v[66:67]
	v_pk_add_f32 v[154:155], v[114:115], v[154:155]
	v_pk_mul_f32 v[194:195], v[170:171], v[170:171]
	v_pk_mul_f32 v[196:197], v[172:173], v[172:173]
	v_pk_mul_f32 v[208:209], v[204:205], v[204:205]
	v_pk_mul_f32 v[210:211], v[206:207], v[206:207]
	v_lshl_add_u64 v[120:121], v[64:65], 0, s[14:15]
	v_lshl_add_u64 v[122:123], v[64:65], 0, s[16:17]
	v_lshl_add_u64 v[64:65], v[120:121], 0, v[132:133]
	v_lshl_add_u64 v[68:69], v[122:123], 0, v[132:133]
	v_lshl_add_u64 v[72:73], v[120:121], 0, v[140:141]
	v_lshl_add_u64 v[76:77], v[122:123], 0, v[140:141]
	v_lshl_add_u64 v[80:81], v[120:121], 0, v[142:143]
	v_lshl_add_u64 v[84:85], v[122:123], 0, v[142:143]
	v_lshl_add_u64 v[88:89], v[120:121], 0, v[144:145]
	v_lshl_add_u64 v[92:93], v[122:123], 0, v[144:145]
	v_lshl_add_u64 v[96:97], v[120:121], 0, v[146:147]
	v_lshl_add_u64 v[100:101], v[122:123], 0, v[146:147]
	v_lshl_add_u64 v[104:105], v[120:121], 0, v[148:149]
	v_lshl_add_u64 v[108:109], v[122:123], 0, v[148:149]
	v_lshl_add_u64 v[112:113], v[120:121], 0, v[150:151]
	v_lshl_add_u64 v[116:117], v[122:123], 0, v[150:151]
	v_lshl_add_u64 v[120:121], v[120:121], 0, v[152:153]
	v_lshl_add_u64 v[124:125], v[122:123], 0, v[152:153]
	global_load_dwordx4 v[64:67], v[64:65], off
	s_nop 0
	global_load_dwordx4 v[68:71], v[68:69], off
	s_nop 0
	global_load_dwordx4 v[72:75], v[72:73], off
	s_nop 0
	global_load_dwordx4 v[76:79], v[76:77], off
	s_nop 0
	global_load_dwordx4 v[80:83], v[80:81], off
	s_nop 0
	global_load_dwordx4 v[84:87], v[84:85], off
	s_nop 0
	global_load_dwordx4 v[88:91], v[88:89], off
	s_nop 0
	global_load_dwordx4 v[92:95], v[92:93], off
	s_nop 0
	global_load_dwordx4 v[96:99], v[96:97], off
	s_nop 0
	global_load_dwordx4 v[100:103], v[100:101], off
	s_nop 0
	global_load_dwordx4 v[104:107], v[104:105], off
	s_nop 0
	global_load_dwordx4 v[108:111], v[108:109], off
	s_nop 0
	global_load_dwordx4 v[112:115], v[112:113], off
	s_nop 0
	global_load_dwordx4 v[116:119], v[116:117], off
	s_nop 0
	global_load_dwordx4 v[120:123], v[120:121], off
	s_nop 0
	global_load_dwordx4 v[124:127], v[124:125], off
	v_mov_b32_e32 v216, v157
	v_mov_b32_e32 v217, v161
	v_mov_b32_e32 v212, v155
	v_mov_b32_e32 v213, v159
	v_mov_b32_e32 v214, v156
	v_mov_b32_e32 v215, v160
	v_pk_mul_f32 v[216:217], v[216:217], v[216:217]
	v_pk_mul_f32 v[212:213], v[212:213], v[212:213]
	v_pk_fma_f32 v[214:215], v[214:215], v[214:215], v[216:217]
	v_mov_b32_e32 v216, v154
	v_mov_b32_e32 v217, v158
	v_pk_fma_f32 v[212:213], v[216:217], v[216:217], v[212:213]
	v_mov_b32_e32 v191, v196
	v_pk_add_f32 v[212:213], v[212:213], v[214:215]
	v_mov_b32_e32 v193, v197
	v_pk_add_f32 v[212:213], v[212:213], v[212:213] op_sel:[0,1] op_sel_hi:[1,0]
	v_mov_b32_e32 v177, v195
	v_mov_b32_e32 v213, v194
	v_pk_add_f32 v[190:191], v[190:191], v[192:193]
	v_pk_add_f32 v[176:177], v[212:213], v[176:177]
	v_mov_b32_e32 v201, v210
	v_pk_add_f32 v[176:177], v[176:177], v[190:191]
	v_mov_b32_e32 v203, v211
	v_pk_add_f32 v[176:177], v[176:177], v[176:177] op_sel:[0,1] op_sel_hi:[1,0]
	v_mov_b32_e32 v199, v209
	v_mov_b32_e32 v177, v208
	v_pk_add_f32 v[190:191], v[200:201], v[202:203]
	v_pk_add_f32 v[176:177], v[176:177], v[198:199]
	s_nop 0
	v_pk_add_f32 v[176:177], v[176:177], v[190:191]
	s_nop 0
	v_add_f32_e32 v176, v176, v177
	ds_bpermute_b32 v177, v129, v176
	s_waitcnt lgkmcnt(0)
	v_add_f32_e32 v176, v176, v177
	ds_bpermute_b32 v177, v184, v176
	s_waitcnt lgkmcnt(0)
	v_add_f32_e32 v176, v176, v177
	ds_bpermute_b32 v177, v185, v176
	s_waitcnt lgkmcnt(0)
	v_add_f32_e32 v176, v176, v177
	ds_bpermute_b32 v177, v186, v176
	s_waitcnt lgkmcnt(0)
	v_add_f32_e32 v176, v176, v177
	ds_bpermute_b32 v177, v187, v176
	s_waitcnt lgkmcnt(0)
	v_add_f32_e32 v176, v176, v177
	ds_bpermute_b32 v177, v188, v176
	s_waitcnt lgkmcnt(0)
	v_add_f32_e32 v176, v176, v177
	v_fmamk_f32 v176, v176, 0x3a000000, v131
	v_mul_f32_e32 v177, 0x4b800000, v176
	v_cmp_gt_f32_e32 vcc, s22, v176
	s_nop 1
	v_cndmask_b32_e32 v176, v176, v177, vcc
	v_rsq_f32_e32 v176, v176
	s_nop 0
	v_mul_f32_e32 v177, 0x45800000, v176
	v_cndmask_b32_e32 v176, v176, v177, vcc
	v_pk_mul_f32 v[158:159], v[158:159], v[176:177] op_sel_hi:[1,0]
	v_pk_mul_f32 v[160:161], v[160:161], v[176:177] op_sel_hi:[1,0]
	v_pk_fma_f32 v[24:25], v[32:33], v[158:159], v[24:25]
	v_pk_fma_f32 v[26:27], v[34:35], v[160:161], v[26:27]
	v_pk_mul_f32 v[32:33], v[180:181], v[176:177] op_sel_hi:[1,0]
	v_pk_mul_f32 v[34:35], v[182:183], v[176:177] op_sel_hi:[1,0]
	v_pk_mul_f32 v[154:155], v[154:155], v[176:177] op_sel_hi:[1,0]
	v_pk_mul_f32 v[156:157], v[156:157], v[176:177] op_sel_hi:[1,0]
	s_waitcnt vmcnt(17)
	v_pk_fma_f32 v[6:7], v[62:63], v[34:35], v[6:7]
	v_pk_fma_f32 v[4:5], v[60:61], v[32:33], v[4:5]
	v_pk_mul_f32 v[32:33], v[204:205], v[176:177] op_sel_hi:[1,0]
	v_pk_mul_f32 v[34:35], v[206:207], v[176:177] op_sel_hi:[1,0]
	v_pk_mul_f32 v[162:163], v[162:163], v[176:177] op_sel_hi:[1,0]
	v_pk_mul_f32 v[164:165], v[164:165], v[176:177] op_sel_hi:[1,0]
	v_pk_mul_f32 v[166:167], v[166:167], v[176:177] op_sel_hi:[1,0]
	v_pk_mul_f32 v[168:169], v[168:169], v[176:177] op_sel_hi:[1,0]
	v_pk_mul_f32 v[170:171], v[170:171], v[176:177] op_sel_hi:[1,0]
	v_pk_mul_f32 v[172:173], v[172:173], v[176:177] op_sel_hi:[1,0]
	v_pk_mul_f32 v[174:175], v[174:175], v[176:177] op_sel_hi:[1,0]
	v_pk_mul_f32 v[178:179], v[178:179], v[176:177] op_sel_hi:[1,0]
	v_pk_fma_f32 v[30:31], v[38:39], v[156:157], v[30:31]
	v_pk_fma_f32 v[28:29], v[36:37], v[154:155], v[28:29]
	s_waitcnt vmcnt(16)
	v_pk_fma_f32 v[2:3], v[50:51], v[34:35], v[2:3]
	v_pk_fma_f32 v[0:1], v[48:49], v[32:33], v[0:1]
	v_pk_fma_f32 v[22:23], v[46:47], v[164:165], v[22:23]
	v_pk_fma_f32 v[20:21], v[44:45], v[162:163], v[20:21]
	v_pk_fma_f32 v[18:19], v[42:43], v[168:169], v[18:19]
	v_pk_fma_f32 v[16:17], v[40:41], v[166:167], v[16:17]
	v_pk_fma_f32 v[14:15], v[58:59], v[172:173], v[14:15]
	v_pk_fma_f32 v[12:13], v[56:57], v[170:171], v[12:13]
	v_pk_fma_f32 v[10:11], v[54:55], v[178:179], v[10:11]
	v_pk_fma_f32 v[8:9], v[52:53], v[174:175], v[8:9]
	global_store_dwordx4 v[136:137], v[28:31], off offset:-4096
	global_store_dwordx4 v[136:137], v[24:27], off offset:-3072
	global_store_dwordx4 v[136:137], v[20:23], off offset:-2048
	global_store_dwordx4 v[136:137], v[16:19], off offset:-1024
	global_store_dwordx4 v[136:137], v[12:15], off
	global_store_dwordx4 v[136:137], v[8:11], off offset:1024
	global_store_dwordx4 v[136:137], v[4:7], off offset:2048
	global_store_dwordx4 v[136:137], v[0:3], off offset:3072
	v_mov_b32_e32 v34, v29
	v_mov_b32_e32 v35, v25
	v_mov_b32_e32 v38, v31
	v_mov_b32_e32 v39, v27
	v_mov_b32_e32 v32, v28
	v_mov_b32_e32 v33, v24
	v_mov_b32_e32 v36, v30
	v_mov_b32_e32 v37, v26
	v_pk_mul_f32 v[40:41], v[22:23], v[22:23]
	v_pk_mul_f32 v[42:43], v[20:21], v[20:21]
	v_pk_mul_f32 v[34:35], v[34:35], v[34:35]
	v_pk_mul_f32 v[38:39], v[38:39], v[38:39]
	v_pk_mov_b32 v[58:59], v[42:43], v[40:41] op_sel:[1,0]
	v_mov_b32_e32 v43, v41
	v_pk_fma_f32 v[32:33], v[32:33], v[32:33], v[34:35]
	v_pk_fma_f32 v[34:35], v[36:37], v[36:37], v[38:39]
	v_mul_f32_e32 v44, v16, v16
	v_mul_f32_e32 v46, v18, v18
	v_pk_add_f32 v[36:37], v[58:59], v[42:43]
	v_pk_add_f32 v[32:33], v[32:33], v[34:35]
	v_pk_fma_f32 v[40:41], v[16:17], v[16:17], v[44:45] op_sel_hi:[1,1,0]
	v_pk_fma_f32 v[44:45], v[18:19], v[18:19], v[46:47] op_sel_hi:[1,1,0]
	v_pk_add_f32 v[34:35], v[36:37], v[36:37] op_sel_hi:[0,1]
	v_pk_add_f32 v[32:33], v[32:33], v[32:33] op_sel_hi:[0,1]
	v_pk_mul_f32 v[48:49], v[10:11], v[10:11]
	v_pk_mul_f32 v[50:51], v[8:9], v[8:9]
	v_mul_f32_e32 v40, v12, v12
	v_mul_f32_e32 v44, v13, v13
	v_mul_f32_e32 v34, v14, v14
	v_mul_f32_e32 v32, v15, v15
	v_pk_mov_b32 v[46:47], v[50:51], v[48:49] op_sel:[1,0]
	v_mov_b32_e32 v51, v49
	v_pk_add_f32 v[36:37], v[40:41], v[44:45]
	v_pk_add_f32 v[32:33], v[34:35], v[32:33]
	v_mul_f32_e32 v52, v4, v4
	v_mul_f32_e32 v54, v6, v6
	v_pk_add_f32 v[38:39], v[46:47], v[50:51]
	v_pk_add_f32 v[32:33], v[36:37], v[32:33]
	v_pk_fma_f32 v[48:49], v[4:5], v[4:5], v[52:53] op_sel_hi:[1,1,0]
	v_pk_fma_f32 v[52:53], v[6:7], v[6:7], v[54:55] op_sel_hi:[1,1,0]
	v_pk_add_f32 v[38:39], v[38:39], v[38:39] op_sel_hi:[0,1]
	v_pk_add_f32 v[32:33], v[32:33], v[32:33] op_sel_hi:[0,1]
	v_mul_f32_e32 v48, v0, v0
	v_mul_f32_e32 v52, v1, v1
	v_mul_f32_e32 v38, v2, v2
	v_mul_f32_e32 v32, v3, v3
	v_pk_add_f32 v[40:41], v[48:49], v[52:53]
	v_pk_add_f32 v[32:33], v[38:39], v[32:33]
	v_add_co_u32_e32 v56, vcc, s23, v134
	v_pk_add_f32 v[32:33], v[40:41], v[32:33]
	s_nop 0
	v_addc_co_u32_e32 v57, vcc, -1, v135, vcc
	v_add_f32_e32 v32, v32, v33
	ds_bpermute_b32 v33, v129, v32
	v_readfirstlane_b32 s83, v237
	s_lshl_b32 s83, s83, 1
	s_add_u32 s83, s83, s86
	s_add_u32 s83, s83, s94
	s_lshl_b32 s83, s83, 3
	s_sub_u32 s84, s83, s82
	s_mov_b32 s82, s83
	s_mov_b32 s85, 0
	s_mov_b32 s2, s84
	s_lshl_b64 s[6:7], s[84:85], 12
	s_lshl_b64 s[8:9], s[84:85], 13
	v_add_u32_e32 v130, s2, v130
	v_cmp_lt_i32_e32 vcc, s24, v130
	s_or_b64 s[10:11], vcc, s[10:11]
	v_lshl_add_u64 v[134:135], v[134:135], 0, s[6:7]
	s_waitcnt lgkmcnt(0)
	v_add_f32_e32 v32, v32, v33
	ds_bpermute_b32 v33, v184, v32
	v_lshl_add_u64 v[136:137], v[136:137], 0, s[8:9]
	s_waitcnt lgkmcnt(0)
	v_add_f32_e32 v32, v32, v33
	ds_bpermute_b32 v33, v185, v32
	s_waitcnt lgkmcnt(0)
	v_add_f32_e32 v32, v32, v33
	ds_bpermute_b32 v33, v186, v32
	s_waitcnt lgkmcnt(0)
	v_add_f32_e32 v32, v32, v33
	ds_bpermute_b32 v33, v187, v32
	s_waitcnt lgkmcnt(0)
	v_add_f32_e32 v32, v32, v33
	ds_bpermute_b32 v33, v188, v32
	s_waitcnt lgkmcnt(0)
	v_add_f32_e32 v32, v32, v33
	v_fmamk_f32 v32, v32, 0x3a000000, v131
	v_mul_f32_e32 v33, 0x4b800000, v32
	v_cmp_gt_f32_e32 vcc, s22, v32
	s_nop 1
	v_cndmask_b32_e32 v32, v32, v33, vcc
	v_rsq_f32_e32 v32, v32
	s_nop 0
	v_mul_f32_e32 v33, 0x45800000, v32
	v_cndmask_b32_e32 v32, v32, v33, vcc
	v_pk_mul_f32 v[28:29], v[28:29], v[32:33] op_sel_hi:[1,0]
	v_pk_mul_f32 v[30:31], v[30:31], v[32:33] op_sel_hi:[1,0]
	v_pk_mul_f32 v[24:25], v[24:25], v[32:33] op_sel_hi:[1,0]
	v_pk_mul_f32 v[26:27], v[26:27], v[32:33] op_sel_hi:[1,0]
	v_pk_mul_f32 v[20:21], v[20:21], v[32:33] op_sel_hi:[1,0]
	v_pk_mul_f32 v[22:23], v[22:23], v[32:33] op_sel_hi:[1,0]
	v_pk_mul_f32 v[16:17], v[16:17], v[32:33] op_sel_hi:[1,0]
	v_pk_mul_f32 v[18:19], v[18:19], v[32:33] op_sel_hi:[1,0]
	v_pk_mul_f32 v[12:13], v[12:13], v[32:33] op_sel_hi:[1,0]
	v_pk_mul_f32 v[14:15], v[14:15], v[32:33] op_sel_hi:[1,0]
	v_pk_mul_f32 v[8:9], v[8:9], v[32:33] op_sel_hi:[1,0]
	v_pk_mul_f32 v[10:11], v[10:11], v[32:33] op_sel_hi:[1,0]
	v_pk_mul_f32 v[4:5], v[4:5], v[32:33] op_sel_hi:[1,0]
	v_pk_mul_f32 v[6:7], v[6:7], v[32:33] op_sel_hi:[1,0]
	v_pk_mul_f32 v[0:1], v[0:1], v[32:33] op_sel_hi:[1,0]
	v_pk_mul_f32 v[2:3], v[2:3], v[32:33] op_sel_hi:[1,0]
	s_waitcnt vmcnt(22)
	v_pk_fma_f32 v[30:31], v[66:67], v[30:31], v[70:71]
	v_pk_fma_f32 v[28:29], v[64:65], v[28:29], v[68:69]
	s_waitcnt vmcnt(20)
	v_pk_fma_f32 v[26:27], v[74:75], v[26:27], v[78:79]
	v_pk_fma_f32 v[24:25], v[72:73], v[24:25], v[76:77]
	s_waitcnt vmcnt(18)
	v_pk_fma_f32 v[22:23], v[82:83], v[22:23], v[86:87]
	v_pk_fma_f32 v[20:21], v[80:81], v[20:21], v[84:85]
	s_waitcnt vmcnt(16)
	v_pk_fma_f32 v[18:19], v[90:91], v[18:19], v[94:95]
	v_pk_fma_f32 v[16:17], v[88:89], v[16:17], v[92:93]
	s_waitcnt vmcnt(14)
	v_pk_fma_f32 v[14:15], v[98:99], v[14:15], v[102:103]
	v_pk_fma_f32 v[12:13], v[96:97], v[12:13], v[100:101]
	s_waitcnt vmcnt(12)
	v_pk_fma_f32 v[10:11], v[106:107], v[10:11], v[110:111]
	v_pk_fma_f32 v[8:9], v[104:105], v[8:9], v[108:109]
	s_waitcnt vmcnt(10)
	v_pk_fma_f32 v[6:7], v[114:115], v[6:7], v[118:119]
	v_pk_fma_f32 v[4:5], v[112:113], v[4:5], v[116:117]
	s_waitcnt vmcnt(8)
	v_pk_fma_f32 v[2:3], v[122:123], v[2:3], v[126:127]
	v_pk_fma_f32 v[0:1], v[120:121], v[0:1], v[124:125]
	v_cvt_pk_bf16_f32 v28, v28, v29
	v_cvt_pk_bf16_f32 v29, v30, v31
	v_cvt_pk_bf16_f32 v24, v24, v25
	v_cvt_pk_bf16_f32 v25, v26, v27
	v_cvt_pk_bf16_f32 v20, v20, v21
	v_cvt_pk_bf16_f32 v21, v22, v23
	v_cvt_pk_bf16_f32 v16, v16, v17
	v_cvt_pk_bf16_f32 v17, v18, v19
	v_cvt_pk_bf16_f32 v12, v12, v13
	v_cvt_pk_bf16_f32 v13, v14, v15
	v_cvt_pk_bf16_f32 v8, v8, v9
	v_cvt_pk_bf16_f32 v9, v10, v11
	v_cvt_pk_bf16_f32 v4, v4, v5
	v_cvt_pk_bf16_f32 v5, v6, v7
	v_cvt_pk_bf16_f32 v0, v0, v1
	v_cvt_pk_bf16_f32 v1, v2, v3
	global_store_dwordx2 v[56:57], v[28:29], off offset:-3584
	global_store_dwordx2 v[56:57], v[24:25], off offset:-3072
	global_store_dwordx2 v[56:57], v[20:21], off offset:-2560
	global_store_dwordx2 v[56:57], v[16:17], off offset:-2048
	global_store_dwordx2 v[56:57], v[12:13], off offset:-1536
	global_store_dwordx2 v[56:57], v[8:9], off offset:-1024
	global_store_dwordx2 v[56:57], v[4:5], off offset:-512
	global_store_dwordx2 v[56:57], v[0:1], off
	s_andn2_b64 exec, exec, s[10:11]
	s_cbranch_execnz .LBB0_1625

.LBB0_1828:
	v_lshrrev_b32_e32 v0, 6, v128
	v_lshl_add_u32 v64, s34, 3, v0
	v_lshlrev_b32_e32 v236, 8, v0
	v_add_u32_e32 v236, 0x2480, v236
	s_and_b32 s86, s34, 1
	s_lshl_b32 s83, s86, 11
	v_add_u32_e32 v236, s83, v236
	s_lshl_b32 s82, s34, 3
	s_movk_i32 s0, 0x2400
	v_cmp_gt_i32_e32 vcc, s0, v64
	s_and_saveexec_b64 s[0:1], vcc
	s_cbranch_execz .LBB0_1831
	v_mbcnt_lo_u32_b32 v1, -1, 0
	v_mbcnt_hi_u32_b32 v1, -1, v1
	s_waitcnt vmcnt(0)
	v_and_b32_e32 v2, 64, v1
	v_add_u32_e32 v2, 64, v2
	v_xor_b32_e32 v3, 1, v1
	v_cmp_lt_i32_e32 vcc, v3, v2
	v_ashrrev_i32_e32 v65, 31, v64
	v_lshlrev_b64 v[16:17], 12, v[64:65]
	v_cndmask_b32_e32 v3, v1, v3, vcc
	v_lshlrev_b32_e32 v130, 2, v3
	v_xor_b32_e32 v3, 2, v1
	v_cmp_lt_i32_e32 vcc, v3, v2
	s_mov_b64 s[2:3], 0x1ce05e00
	v_lshlrev_b32_e32 v0, 2, v128
	v_cndmask_b32_e32 v3, v1, v3, vcc
	v_lshlrev_b32_e32 v131, 2, v3
	v_xor_b32_e32 v3, 4, v1
	v_cmp_lt_i32_e32 vcc, v3, v2
	s_lshl_b32 s0, s94, 3
	v_and_b32_e32 v0, 0xfc, v0
	v_cndmask_b32_e32 v3, v1, v3, vcc
	v_lshlrev_b32_e32 v132, 2, v3
	v_xor_b32_e32 v3, 8, v1
	v_cmp_lt_i32_e32 vcc, v3, v2
	v_mov_b32_e32 v67, 0
	v_or_b32_e32 v4, 0x200, v0
	v_cndmask_b32_e32 v3, v1, v3, vcc
	v_lshlrev_b32_e32 v133, 2, v3
	v_xor_b32_e32 v3, 16, v1
	v_cmp_lt_i32_e32 vcc, v3, v2
	v_or_b32_e32 v6, 0x300, v0
	v_or_b32_e32 v8, 0x400, v0
	v_cndmask_b32_e32 v3, v1, v3, vcc
	v_lshlrev_b32_e32 v134, 2, v3
	v_xor_b32_e32 v3, 32, v1
	v_cmp_lt_i32_e32 vcc, v3, v2
	v_or_b32_e32 v2, 0x100, v0
	v_or_b32_e32 v10, 0x500, v0
	v_cndmask_b32_e32 v1, v1, v3, vcc
	v_lshlrev_b32_e32 v135, 2, v1
	v_and_b32_e32 v1, 63, v128
	v_lshl_or_b32 v16, v1, 3, v16
	v_lshl_add_u64 v[16:17], s[50:51], 0, v[16:17]
	v_lshl_add_u64 v[68:69], v[16:17], 0, s[2:3]
	v_lshlrev_b64 v[16:17], 13, v[64:65]
	v_lshl_or_b32 v16, v1, 4, v16
	v_or_b32_e32 v12, 0x600, v0
	v_or_b32_e32 v14, 0x700, v0
	s_ashr_i32 s1, s0, 31
	v_lshl_add_u64 v[16:17], s[48:49], 0, v[16:17]
	s_mov_b64 s[4:5], 0x1000
	s_lshl_b64 s[2:3], s[0:1], 12
	v_lshl_add_u64 v[70:71], v[16:17], 0, s[4:5]
	s_lshl_b64 s[4:5], s[0:1], 13
	s_mov_b64 s[6:7], 0
	s_movk_i32 s1, 0x2000
	s_mov_b32 s10, 0x12000
	v_mov_b64_e32 v[72:73], s[50:51]
	s_mov_b64 s[8:9], 0xc614000
	s_mov_b32 s11, 0xf3100000
	s_mov_b32 s12, 0xf5500000
	s_mov_b32 s13, 0xfdc00000
	v_lshlrev_b32_e32 v66, 2, v0
	v_lshlrev_b32_e32 v74, 2, v2
	v_mov_b32_e32 v75, v67
	v_lshlrev_b32_e32 v76, 2, v4
	v_mov_b32_e32 v77, v67
	v_lshlrev_b32_e32 v78, 2, v6
	v_mov_b32_e32 v79, v67
	v_lshlrev_b32_e32 v80, 2, v8
	v_mov_b32_e32 v81, v67
	v_lshlrev_b32_e32 v82, 2, v10
	v_mov_b32_e32 v83, v67
	v_lshlrev_b32_e32 v84, 2, v12
	v_mov_b32_e32 v85, v67
	v_lshlrev_b32_e32 v86, 2, v14
	v_mov_b32_e32 v87, v67
	v_mov_b32_e32 v65, 0x358637bd
	s_mov_b32 s14, 0x800000
	s_movk_i32 s15, 0x23ff
.LBB0_1830:
	s_mov_b64 s[80:81], exec
	s_mov_b64 exec, 1
	v_mov_b32_e32 v237, 1
	global_atomic_add v237, v236, v237, s[50:51] sc0
	s_mov_b64 exec, s[80:81]
	global_load_dwordx4 v[28:31], v[70:71], off offset:-4096
	global_load_dwordx4 v[24:27], v[70:71], off offset:-3072
	global_load_dwordx4 v[20:23], v[70:71], off offset:-2048
	global_load_dwordx4 v[16:19], v[70:71], off offset:-1024
	global_load_dwordx4 v[12:15], v[70:71], off
	global_load_dwordx4 v[8:11], v[70:71], off offset:1024
	global_load_dwordx4 v[4:7], v[70:71], off offset:2048
	global_load_dwordx4 v[0:3], v[70:71], off offset:3072
	v_add_u32_e32 v33, 0xffffe000, v64
	v_lshrrev_b32_e32 v33, 3, v33
	v_ashrrev_i32_e32 v32, 12, v64
	v_add_u32_e32 v33, 2, v33
	v_cmp_gt_i32_e32 vcc, s1, v64
	s_nop 1
	v_cndmask_b32_e32 v32, v33, v32, vcc
	v_mad_i64_i32 v[32:33], s[16:17], v32, s10, v[72:73]
	v_add_co_u32_e32 v50, vcc, s11, v68
	v_lshl_add_u64 v[48:49], v[32:33], 0, s[8:9]
	s_nop 0
	v_addc_co_u32_e32 v51, vcc, -1, v69, vcc
	v_add_co_u32_e32 v60, vcc, s12, v68
	v_lshl_add_u64 v[40:41], v[48:49], 0, v[66:67]
	s_nop 0
	v_addc_co_u32_e32 v61, vcc, -1, v69, vcc
	v_add_co_u32_e32 v62, vcc, s13, v68
	v_lshl_add_u64 v[42:43], v[48:49], 0, v[74:75]
	v_lshl_add_u64 v[52:53], v[48:49], 0, v[76:77]
	v_lshl_add_u64 v[54:55], v[48:49], 0, v[78:79]
	v_addc_co_u32_e32 v63, vcc, -1, v69, vcc
	global_load_dwordx4 v[36:39], v[40:41], off
	global_load_dwordx4 v[32:35], v[42:43], off
	global_load_dwordx2 v[90:91], v[50:51], off offset:-3584
	global_load_dwordx2 v[102:103], v[50:51], off offset:-3072
	global_load_dwordx2 v[114:115], v[50:51], off offset:-2560
	global_load_dwordx2 v[126:127], v[50:51], off offset:-2048
	global_load_dwordx2 v[100:101], v[60:61], off offset:-3584
	global_load_dwordx2 v[112:113], v[60:61], off offset:-3072
	global_load_dwordx2 v[116:117], v[60:61], off offset:-2560
	global_load_dwordx2 v[128:129], v[60:61], off offset:-2048
	global_load_dwordx2 v[136:137], v[62:63], off offset:-3584
	global_load_dwordx2 v[138:139], v[62:63], off offset:-3072
	global_load_dwordx2 v[140:141], v[62:63], off offset:-2560
	global_load_dwordx2 v[142:143], v[62:63], off offset:-2048
	global_load_dwordx2 v[144:145], v[68:69], off offset:-3584
	global_load_dwordx2 v[146:147], v[68:69], off offset:-3072
	global_load_dwordx2 v[148:149], v[68:69], off offset:-2560
	global_load_dwordx2 v[150:151], v[68:69], off offset:-2048
	global_load_dwordx4 v[44:47], v[52:53], off
	global_load_dwordx4 v[40:43], v[54:55], off
	v_lshl_add_u64 v[52:53], v[48:49], 0, v[80:81]
	v_lshl_add_u64 v[54:55], v[48:49], 0, v[82:83]
	global_load_dwordx4 v[56:59], v[52:53], off
	s_nop 0
	global_load_dwordx4 v[52:55], v[54:55], off
	s_nop 0
	global_load_dwordx2 v[152:153], v[50:51], off offset:-1536
	global_load_dwordx2 v[118:119], v[50:51], off offset:-1024
	global_load_dwordx2 v[104:105], v[50:51], off offset:-512
	global_load_dwordx2 v[96:97], v[50:51], off
	global_load_dwordx2 v[154:155], v[60:61], off offset:-1536
	global_load_dwordx2 v[124:125], v[60:61], off offset:-1024
	global_load_dwordx2 v[110:111], v[60:61], off offset:-512
	global_load_dwordx2 v[98:99], v[60:61], off
	global_load_dwordx2 v[156:157], v[62:63], off offset:-1536
	global_load_dwordx2 v[120:121], v[62:63], off offset:-1024
	global_load_dwordx2 v[106:107], v[62:63], off offset:-512
	global_load_dwordx2 v[92:93], v[62:63], off
	global_load_dwordx2 v[158:159], v[68:69], off offset:-1536
	global_load_dwordx2 v[122:123], v[68:69], off offset:-1024
	global_load_dwordx2 v[108:109], v[68:69], off offset:-512
	global_load_dwordx2 v[94:95], v[68:69], off
	v_lshl_add_u64 v[88:89], v[48:49], 0, v[84:85]
	v_lshl_add_u64 v[48:49], v[48:49], 0, v[86:87]
	global_load_dwordx4 v[60:63], v[88:89], off
	s_nop 0
	global_load_dwordx4 v[48:51], v[48:49], off
	s_waitcnt vmcnt(37)
	v_lshlrev_b32_e32 v88, 16, v90
	v_and_b32_e32 v89, 0xffff0000, v90
	s_waitcnt vmcnt(33)
	v_lshlrev_b32_e32 v160, 16, v100
	v_and_b32_e32 v161, 0xffff0000, v100
	v_lshlrev_b32_e32 v90, 16, v91
	v_and_b32_e32 v91, 0xffff0000, v91
	v_lshlrev_b32_e32 v100, 16, v101
	v_and_b32_e32 v101, 0xffff0000, v101
	v_pk_add_f32 v[88:89], v[88:89], v[160:161]
	s_waitcnt vmcnt(29)
	v_lshlrev_b32_e32 v160, 16, v136
	v_and_b32_e32 v161, 0xffff0000, v136
	v_pk_add_f32 v[90:91], v[90:91], v[100:101]
	v_lshlrev_b32_e32 v100, 16, v137
	v_and_b32_e32 v101, 0xffff0000, v137
	s_waitcnt vmcnt(25)
	v_lshlrev_b32_e32 v136, 16, v145
	v_and_b32_e32 v137, 0xffff0000, v145
	v_pk_add_f32 v[100:101], v[100:101], v[136:137]
	v_lshlrev_b32_e32 v136, 16, v112
	v_pk_add_f32 v[90:91], v[90:91], v[100:101]
	v_lshlrev_b32_e32 v100, 16, v102
	v_and_b32_e32 v101, 0xffff0000, v102
	v_and_b32_e32 v137, 0xffff0000, v112
	v_lshlrev_b32_e32 v162, 16, v144
	v_and_b32_e32 v163, 0xffff0000, v144
	v_pk_add_f32 v[100:101], v[100:101], v[136:137]
	v_lshlrev_b32_e32 v136, 16, v138
	v_and_b32_e32 v137, 0xffff0000, v138
	s_waitcnt vmcnt(24)
	v_lshlrev_b32_e32 v144, 16, v146
	v_and_b32_e32 v145, 0xffff0000, v146
	v_pk_add_f32 v[136:137], v[136:137], v[144:145]
	v_lshlrev_b32_e32 v102, 16, v103
	v_and_b32_e32 v103, 0xffff0000, v103
	v_lshlrev_b32_e32 v112, 16, v113
	v_and_b32_e32 v113, 0xffff0000, v113
	v_pk_add_f32 v[160:161], v[160:161], v[162:163]
	v_pk_add_f32 v[100:101], v[100:101], v[136:137]
	v_pk_add_f32 v[102:103], v[102:103], v[112:113]
	v_lshlrev_b32_e32 v112, 16, v139
	v_and_b32_e32 v113, 0xffff0000, v139
	v_lshlrev_b32_e32 v136, 16, v147
	v_and_b32_e32 v137, 0xffff0000, v147
	v_pk_add_f32 v[88:89], v[88:89], v[160:161]
	v_pk_add_f32 v[112:113], v[112:113], v[136:137]
	v_mov_b32_e32 v136, v89
	v_pk_add_f32 v[102:103], v[102:103], v[112:113]
	v_mov_b32_e32 v137, v101
	v_mov_b32_e32 v112, v88
	v_mov_b32_e32 v113, v100
	v_pk_mul_f32 v[136:137], v[136:137], v[136:137]
	v_mov_b32_e32 v138, v91
	v_mov_b32_e32 v139, v103
	v_pk_fma_f32 v[112:113], v[112:113], v[112:113], v[136:137]
	v_mov_b32_e32 v136, v90
	v_mov_b32_e32 v137, v102
	v_pk_mul_f32 v[138:139], v[138:139], v[138:139]
	s_waitcnt vmcnt(23)
	v_lshlrev_b32_e32 v144, 16, v148
	v_pk_fma_f32 v[136:137], v[136:137], v[136:137], v[138:139]
	v_lshlrev_b32_e32 v138, 16, v116
	v_pk_add_f32 v[112:113], v[112:113], v[136:137]
	v_and_b32_e32 v139, 0xffff0000, v116
	v_pk_add_f32 v[136:137], v[112:113], v[112:113] op_sel:[0,1] op_sel_hi:[1,0]
	v_lshlrev_b32_e32 v112, 16, v114
	v_and_b32_e32 v113, 0xffff0000, v114
	v_pk_add_f32 v[112:113], v[112:113], v[138:139]
	v_lshlrev_b32_e32 v138, 16, v140
	v_and_b32_e32 v139, 0xffff0000, v140
	v_and_b32_e32 v145, 0xffff0000, v148
	v_pk_add_f32 v[138:139], v[138:139], v[144:145]
	v_lshlrev_b32_e32 v114, 16, v115
	v_and_b32_e32 v115, 0xffff0000, v115
	v_lshlrev_b32_e32 v116, 16, v117
	v_and_b32_e32 v117, 0xffff0000, v117
	v_pk_add_f32 v[112:113], v[112:113], v[138:139]
	v_pk_add_f32 v[114:115], v[114:115], v[116:117]
	v_lshlrev_b32_e32 v116, 16, v141
	v_and_b32_e32 v117, 0xffff0000, v141
	v_lshlrev_b32_e32 v138, 16, v149
	v_and_b32_e32 v139, 0xffff0000, v149
	v_pk_add_f32 v[116:117], v[116:117], v[138:139]
	v_mov_b32_e32 v138, v113
	v_pk_add_f32 v[114:115], v[114:115], v[116:117]
	v_mov_b32_e32 v116, v112
	v_mov_b32_e32 v139, v115
	v_mov_b32_e32 v117, v114
	v_pk_mul_f32 v[138:139], v[138:139], v[138:139]
	v_lshlrev_b32_e32 v140, 16, v128
	v_pk_fma_f32 v[116:117], v[116:117], v[116:117], v[138:139]
	v_and_b32_e32 v141, 0xffff0000, v128
	v_pk_add_f32 v[138:139], v[116:117], v[116:117] op_sel:[0,1] op_sel_hi:[1,0]
	v_lshlrev_b32_e32 v116, 16, v126
	v_and_b32_e32 v117, 0xffff0000, v126
	v_pk_add_f32 v[116:117], v[116:117], v[140:141]
	v_lshlrev_b32_e32 v140, 16, v142
	v_and_b32_e32 v141, 0xffff0000, v142
	s_waitcnt vmcnt(22)
	v_lshlrev_b32_e32 v144, 16, v150
	v_and_b32_e32 v145, 0xffff0000, v150
	v_pk_add_f32 v[140:141], v[140:141], v[144:145]
	v_lshlrev_b32_e32 v126, 16, v127
	v_and_b32_e32 v127, 0xffff0000, v127
	v_lshlrev_b32_e32 v128, 16, v129
	v_and_b32_e32 v129, 0xffff0000, v129
	v_pk_add_f32 v[116:117], v[116:117], v[140:141]
	v_pk_add_f32 v[126:127], v[126:127], v[128:129]
	v_lshlrev_b32_e32 v128, 16, v143
	v_and_b32_e32 v129, 0xffff0000, v143
	v_lshlrev_b32_e32 v140, 16, v151
	v_and_b32_e32 v141, 0xffff0000, v151
	v_pk_add_f32 v[128:129], v[128:129], v[140:141]
	s_waitcnt vmcnt(13)
	v_lshlrev_b32_e32 v144, 16, v154
	v_pk_add_f32 v[126:127], v[126:127], v[128:129]
	v_mul_f32_e32 v128, v117, v117
	v_pk_fma_f32 v[140:141], v[116:117], v[116:117], v[128:129] op_sel_hi:[1,1,0]
	v_mul_f32_e32 v128, v127, v127
	v_pk_fma_f32 v[142:143], v[126:127], v[126:127], v[128:129] op_sel_hi:[1,1,0]
	v_lshlrev_b32_e32 v128, 16, v152
	v_and_b32_e32 v129, 0xffff0000, v152
	v_and_b32_e32 v145, 0xffff0000, v154
	v_pk_add_f32 v[128:129], v[128:129], v[144:145]
	s_waitcnt vmcnt(9)
	v_lshlrev_b32_e32 v144, 16, v156
	v_and_b32_e32 v145, 0xffff0000, v156
	s_waitcnt vmcnt(5)
	v_lshlrev_b32_e32 v146, 16, v158
	v_and_b32_e32 v147, 0xffff0000, v158
	v_pk_add_f32 v[144:145], v[144:145], v[146:147]
	v_lshlrev_b32_e32 v146, 16, v155
	v_pk_add_f32 v[128:129], v[128:129], v[144:145]
	v_lshlrev_b32_e32 v144, 16, v153
	v_and_b32_e32 v145, 0xffff0000, v153
	v_and_b32_e32 v147, 0xffff0000, v155
	v_pk_add_f32 v[144:145], v[144:145], v[146:147]
	v_lshlrev_b32_e32 v146, 16, v157
	v_and_b32_e32 v147, 0xffff0000, v157
	v_lshlrev_b32_e32 v148, 16, v159
	v_and_b32_e32 v149, 0xffff0000, v159
	v_pk_add_f32 v[146:147], v[146:147], v[148:149]
	s_nop 0
	v_pk_add_f32 v[144:145], v[144:145], v[146:147]
	v_pk_mul_f32 v[146:147], v[128:129], v[128:129]
	v_pk_mul_f32 v[148:149], v[144:145], v[144:145]
	v_mov_b32_e32 v137, v146
	v_mov_b32_e32 v139, v147
	v_mov_b32_e32 v141, v148
	v_mov_b32_e32 v143, v149
	v_pk_add_f32 v[136:137], v[136:137], v[138:139]
	v_pk_add_f32 v[138:139], v[140:141], v[142:143]
	v_lshlrev_b32_e32 v140, 16, v124
	v_pk_add_f32 v[136:137], v[136:137], v[138:139]
	v_lshlrev_b32_e32 v138, 16, v118
	v_and_b32_e32 v139, 0xffff0000, v118
	v_and_b32_e32 v141, 0xffff0000, v124
	v_pk_add_f32 v[138:139], v[138:139], v[140:141]
	v_lshlrev_b32_e32 v140, 16, v120
	v_and_b32_e32 v141, 0xffff0000, v120
	s_waitcnt vmcnt(4)
	v_lshlrev_b32_e32 v142, 16, v122
	v_and_b32_e32 v143, 0xffff0000, v122
	v_lshlrev_b32_e32 v118, 16, v119
	v_and_b32_e32 v119, 0xffff0000, v119
	v_lshlrev_b32_e32 v124, 16, v125
	v_and_b32_e32 v125, 0xffff0000, v125
	v_lshlrev_b32_e32 v120, 16, v121
	v_and_b32_e32 v121, 0xffff0000, v121
	v_lshlrev_b32_e32 v122, 16, v123
	v_and_b32_e32 v123, 0xffff0000, v123
	v_pk_add_f32 v[140:141], v[140:141], v[142:143]
	v_pk_add_f32 v[118:119], v[118:119], v[124:125]
	v_pk_add_f32 v[120:121], v[120:121], v[122:123]
	v_pk_add_f32 v[138:139], v[138:139], v[140:141]
	v_pk_add_f32 v[118:119], v[118:119], v[120:121]
	v_mov_b32_e32 v122, v139
	v_mov_b32_e32 v123, v119
	v_mov_b32_e32 v120, v138
	v_mov_b32_e32 v121, v118
	v_pk_mul_f32 v[122:123], v[122:123], v[122:123]
	v_lshlrev_b32_e32 v124, 16, v110
	v_pk_fma_f32 v[120:121], v[120:121], v[120:121], v[122:123]
	v_lshlrev_b32_e32 v122, 16, v104
	v_and_b32_e32 v123, 0xffff0000, v104
	v_and_b32_e32 v125, 0xffff0000, v110
	v_pk_add_f32 v[122:123], v[122:123], v[124:125]
	v_lshlrev_b32_e32 v124, 16, v106
	v_and_b32_e32 v125, 0xffff0000, v106
	s_waitcnt vmcnt(3)
	v_lshlrev_b32_e32 v140, 16, v108
	v_and_b32_e32 v141, 0xffff0000, v108
	v_pk_add_f32 v[124:125], v[124:125], v[140:141]
	v_lshlrev_b32_e32 v104, 16, v105
	v_and_b32_e32 v105, 0xffff0000, v105
	v_lshlrev_b32_e32 v110, 16, v111
	v_and_b32_e32 v111, 0xffff0000, v111
	v_pk_add_f32 v[122:123], v[122:123], v[124:125]
	v_pk_add_f32 v[104:105], v[104:105], v[110:111]
	v_lshlrev_b32_e32 v106, 16, v107
	v_and_b32_e32 v107, 0xffff0000, v107
	v_lshlrev_b32_e32 v108, 16, v109
	v_and_b32_e32 v109, 0xffff0000, v109
	v_lshlrev_b32_e32 v110, 16, v96
	v_and_b32_e32 v111, 0xffff0000, v96
	v_lshlrev_b32_e32 v124, 16, v98
	v_and_b32_e32 v125, 0xffff0000, v98
	v_pk_add_f32 v[106:107], v[106:107], v[108:109]
	v_pk_add_f32 v[110:111], v[110:111], v[124:125]
	v_lshlrev_b32_e32 v124, 16, v92
	v_and_b32_e32 v125, 0xffff0000, v92
	s_waitcnt vmcnt(2)
	v_lshlrev_b32_e32 v140, 16, v94
	v_and_b32_e32 v141, 0xffff0000, v94
	v_lshlrev_b32_e32 v96, 16, v97
	v_and_b32_e32 v97, 0xffff0000, v97
	v_lshlrev_b32_e32 v98, 16, v99
	v_and_b32_e32 v99, 0xffff0000, v99
	v_lshlrev_b32_e32 v92, 16, v93
	v_and_b32_e32 v93, 0xffff0000, v93
	v_lshlrev_b32_e32 v94, 16, v95
	v_and_b32_e32 v95, 0xffff0000, v95
	v_pk_add_f32 v[104:105], v[104:105], v[106:107]
	v_pk_add_f32 v[124:125], v[124:125], v[140:141]
	v_pk_add_f32 v[96:97], v[96:97], v[98:99]
	v_pk_add_f32 v[92:93], v[92:93], v[94:95]
	v_mul_f32_e32 v106, v123, v123
	v_mul_f32_e32 v108, v105, v105
	v_pk_add_f32 v[110:111], v[110:111], v[124:125]
	v_pk_add_f32 v[92:93], v[96:97], v[92:93]
	v_pk_add_f32 v[136:137], v[136:137], v[136:137] op_sel:[0,1] op_sel_hi:[1,0]
	v_pk_add_f32 v[120:121], v[120:121], v[120:121] op_sel:[0,1] op_sel_hi:[1,0]
	v_pk_fma_f32 v[106:107], v[122:123], v[122:123], v[106:107] op_sel_hi:[1,1,0]
	v_pk_fma_f32 v[108:109], v[104:105], v[104:105], v[108:109] op_sel_hi:[1,1,0]
	v_pk_mul_f32 v[94:95], v[110:111], v[110:111]
	v_pk_mul_f32 v[96:97], v[92:93], v[92:93]
	v_mov_b32_e32 v137, v94
	v_mov_b32_e32 v121, v95
	v_mov_b32_e32 v107, v96
	v_mov_b32_e32 v109, v97
	v_pk_add_f32 v[94:95], v[136:137], v[120:121]
	v_pk_add_f32 v[96:97], v[106:107], v[108:109]
	s_nop 0
	v_pk_add_f32 v[94:95], v[94:95], v[96:97]
	s_nop 0
	v_add_f32_e32 v94, v94, v95
	ds_bpermute_b32 v95, v130, v94
	s_waitcnt lgkmcnt(0)
	v_add_f32_e32 v94, v94, v95
	ds_bpermute_b32 v95, v131, v94
	s_waitcnt lgkmcnt(0)
	v_add_f32_e32 v94, v94, v95
	ds_bpermute_b32 v95, v132, v94
	s_waitcnt lgkmcnt(0)
	v_add_f32_e32 v94, v94, v95
	ds_bpermute_b32 v95, v133, v94
	s_waitcnt lgkmcnt(0)
	v_add_f32_e32 v94, v94, v95
	ds_bpermute_b32 v95, v134, v94
	s_waitcnt lgkmcnt(0)
	v_add_f32_e32 v94, v94, v95
	ds_bpermute_b32 v95, v135, v94
	s_waitcnt lgkmcnt(0)
	v_add_f32_e32 v94, v94, v95
	v_fmamk_f32 v94, v94, 0x3a000000, v65
	v_mul_f32_e32 v95, 0x4b800000, v94
	v_cmp_gt_f32_e32 vcc, s14, v94
	s_nop 1
	v_cndmask_b32_e32 v94, v94, v95, vcc
	v_rsq_f32_e32 v94, v94
	s_nop 0
	v_mul_f32_e32 v95, 0x45800000, v94
	v_cndmask_b32_e32 v94, v94, v95, vcc
	v_pk_mul_f32 v[88:89], v[88:89], v[94:95] op_sel_hi:[1,0]
	v_pk_mul_f32 v[90:91], v[90:91], v[94:95] op_sel_hi:[1,0]
	v_pk_mul_f32 v[106:107], v[116:117], v[94:95] op_sel_hi:[1,0]
	v_pk_mul_f32 v[116:117], v[138:139], v[94:95] op_sel_hi:[1,0]
	v_pk_mul_f32 v[118:119], v[118:119], v[94:95] op_sel_hi:[1,0]
	v_pk_mul_f32 v[96:97], v[100:101], v[94:95] op_sel_hi:[1,0]
	v_pk_mul_f32 v[98:99], v[102:103], v[94:95] op_sel_hi:[1,0]
	v_pk_mul_f32 v[100:101], v[112:113], v[94:95] op_sel_hi:[1,0]
	v_pk_mul_f32 v[102:103], v[114:115], v[94:95] op_sel_hi:[1,0]
	v_pk_mul_f32 v[108:109], v[126:127], v[94:95] op_sel_hi:[1,0]
	v_pk_mul_f32 v[112:113], v[128:129], v[94:95] op_sel_hi:[1,0]
	v_pk_mul_f32 v[114:115], v[144:145], v[94:95] op_sel_hi:[1,0]
	v_pk_fma_f32 v[30:31], v[38:39], v[90:91], v[30:31]
	v_pk_fma_f32 v[28:29], v[36:37], v[88:89], v[28:29]
	v_pk_fma_f32 v[10:11], v[54:55], v[118:119], v[10:11]
	v_pk_fma_f32 v[8:9], v[52:53], v[116:117], v[8:9]
	v_pk_fma_f32 v[26:27], v[34:35], v[98:99], v[26:27]
	v_pk_fma_f32 v[24:25], v[32:33], v[96:97], v[24:25]
	v_pk_fma_f32 v[22:23], v[46:47], v[102:103], v[22:23]
	v_pk_fma_f32 v[20:21], v[44:45], v[100:101], v[20:21]
	v_pk_fma_f32 v[18:19], v[42:43], v[108:109], v[18:19]
	v_pk_fma_f32 v[16:17], v[40:41], v[106:107], v[16:17]
	v_pk_fma_f32 v[14:15], v[58:59], v[114:115], v[14:15]
	v_pk_fma_f32 v[12:13], v[56:57], v[112:113], v[12:13]
	global_store_dwordx4 v[70:71], v[28:31], off offset:-4096
	global_store_dwordx4 v[70:71], v[24:27], off offset:-3072
	global_store_dwordx4 v[70:71], v[20:23], off offset:-2048
	global_store_dwordx4 v[70:71], v[16:19], off offset:-1024
	global_store_dwordx4 v[70:71], v[12:15], off
	global_store_dwordx4 v[70:71], v[8:11], off offset:1024
	s_nop 1
	v_pk_mul_f32 v[8:9], v[122:123], v[94:95] op_sel_hi:[1,0]
	v_pk_mul_f32 v[10:11], v[104:105], v[94:95] op_sel_hi:[1,0]
	s_waitcnt vmcnt(7)
	v_pk_fma_f32 v[4:5], v[60:61], v[8:9], v[4:5]
	v_pk_fma_f32 v[6:7], v[62:63], v[10:11], v[6:7]
	global_store_dwordx4 v[70:71], v[4:7], off offset:2048
	s_nop 1
	v_pk_mul_f32 v[4:5], v[110:111], v[94:95] op_sel_hi:[1,0]
	v_pk_mul_f32 v[6:7], v[92:93], v[94:95] op_sel_hi:[1,0]
	s_waitcnt vmcnt(7)
	v_pk_fma_f32 v[0:1], v[48:49], v[4:5], v[0:1]
	v_pk_fma_f32 v[2:3], v[50:51], v[6:7], v[2:3]
	global_store_dwordx4 v[70:71], v[0:3], off offset:3072
	s_waitcnt vmcnt(8)
	v_readfirstlane_b32 s83, v237
	s_lshl_b32 s83, s83, 1
	s_add_u32 s83, s83, s86
	s_add_u32 s83, s83, s94
	s_lshl_b32 s83, s83, 3
	s_sub_u32 s84, s83, s82
	s_mov_b32 s82, s83
	s_mov_b32 s85, 0
	s_mov_b32 s0, s84
	s_lshl_b64 s[2:3], s[84:85], 12
	s_lshl_b64 s[4:5], s[84:85], 13
	v_add_u32_e32 v64, s0, v64
	v_cmp_lt_i32_e32 vcc, s15, v64
	v_lshl_add_u64 v[68:69], v[68:69], 0, s[2:3]
	s_or_b64 s[6:7], vcc, s[6:7]
	v_lshl_add_u64 v[70:71], v[70:71], 0, s[4:5]
	s_andn2_b64 exec, exec, s[6:7]
	s_cbranch_execnz .LBB0_1830
